# all 8 GEMM K loops: LDS-DMA stage loads use SGPR base + 32-bit VGPR offset (derived bases by SALU), no VALU in load segments
# speedup vs baseline: 1.0077x; 1.0018x over previous
; #define PG8_STAGE(bufoff, gbase, voff) do { _Pragma("unroll") for (int _i = 0; _i < 2; ++_i) \
;         __builtin_amdgcn_global_load_lds((const unsigned*)((const char*)(gbase) + (voff)[_i]), (PG8_LAS unsigned*)(lds + (bufoff) + ldsw + _i * 8192), 16, 0, 0); } while (0)
; #define PG8_LDA(dst, b, h) do { _Pragma("unroll") for (int m = 0; m < 4; ++m) _Pragma("unroll") for (int k = 0; k < 2; ++k) dst[m][k] = *(const PG8_LAS bf16x8*)(lds + PG8_SA(b, h) + aoff + m * 2048 + k * 1024); } while (0)
; #define PG8_LDB(dst, b, h) do { _Pragma("unroll") for (int n = 0; n < 2; ++n) _Pragma("unroll") for (int k = 0; k < 2; ++k) dst[n][k] = *(const PG8_LAS bf16x8*)(lds + PG8_SB(b, h) + boff + n * 2048 + k * 1024); } while (0)
; #define PG8_MMA(ai, bj, At, Bt) do { __builtin_amdgcn_s_setprio(1); _Pragma("unroll") for (int m = 0; m < 4; ++m) _Pragma("unroll") for (int n = 0; n < 2; ++n) _Pragma("unroll") for (int k = 0; k < 2; ++k) \
;         acc[ai][bj][m][n] = __builtin_amdgcn_mfma_f32_16x16x32_bf16(Bt[n][k], At[m][k], acc[ai][bj][m][n], 0, 0, 0); __builtin_amdgcn_s_setprio(0); } while (0)
; #define PG8_WAIT_V(n) asm volatile("s_waitcnt vmcnt(" #n ")" ::: "memory")
; #define PG8_WAIT_L(n) asm volatile("s_waitcnt lgkmcnt(" #n ")" ::: "memory")
; #define PG8_BAR __builtin_amdgcn_s_barrier()
; #define PG8_SCHED __builtin_amdgcn_sched_barrier(0)
; template <class Epi, class Sched, bool ALIGN_EPI = false, bool SP2 = false>
; __device__ __forceinline__ void gemm_phase(PG8_LAS unsigned char* lds, const Gemm g, const Sched& S, const Epi& E) {
;     ...
;             PG8_LDB(B0, 0, 0); PG8_LDB(B1, 0, 1); PG8_SCHED; PG8_LDA(At, 0, 0); PG8_STAGE(PG8_SA(1, 1), a1 + hstep, voffA);
;             PG8_WAIT_V(8); PG8_WAIT_L(0); PG8_BAR; PG8_MMA(0, 0, At, B0); PG8_MMA(0, 1, At, B1); PG8_BAR; PG8_SCHED;
;             PG8_LDA(At, 0, 1); PG8_STAGE(PG8_SB(0, 0), b2, voffB); PG8_STAGE(PG8_SB(0, 1), b2 + hstep, voffB); PG8_STAGE(PG8_SA(0, 0), a2, voffA);
;             PG8_WAIT_V(8); PG8_WAIT_L(0); PG8_BAR; PG8_MMA(1, 0, At, B0); PG8_MMA(1, 1, At, B1); PG8_BAR; PG8_SCHED;
.LBB0_381:
	ds_read_b128 v[144:147], v151
	ds_read_b128 v[156:159], v151 offset:1024
	ds_read_b128 v[160:163], v151 offset:2048
	ds_read_b128 v[164:167], v151 offset:3072
	ds_read_b128 v[168:171], v153
	ds_read_b128 v[172:175], v153 offset:1024
	ds_read_b128 v[176:179], v153 offset:2048
	ds_read_b128 v[180:183], v153 offset:3072
	s_add_u32 s33, s42, 0xfffc0080
	s_addc_u32 s34, s43, -1
	s_cmp_eq_u32 s86, 12
	s_cselect_b32 s47, s23, s34
	s_cselect_b32 s46, s80, s33
	s_cselect_b32 s45, s21, s83
	s_cselect_b32 s44, s81, s82
	s_add_i32 m0, s41, 0xc000
	ds_read_b128 v[184:187], v154
	ds_read_b128 v[188:191], v154 offset:1024
	ds_read_b128 v[192:195], v154 offset:2048
	ds_read_b128 v[196:199], v154 offset:3072
	ds_read_b128 v[200:203], v154 offset:4096
	ds_read_b128 v[204:207], v154 offset:5120
	ds_read_b128 v[208:211], v154 offset:6144
	ds_read_b128 v[212:215], v154 offset:7168
	global_load_lds_dwordx4 v136, s[42:43]
	s_add_i32 m0, s41, 0xe000
	s_nop 0
	global_load_lds_dwordx4 v138, s[42:43]
	s_waitcnt vmcnt(8)
	s_waitcnt lgkmcnt(0)
	s_barrier
	s_setprio 1
	s_waitcnt lgkmcnt(0)
	v_mfma_f32_16x16x32_bf16 v[124:127], v[144:147], v[184:187], v[124:127]
	v_mfma_f32_16x16x32_bf16 v[120:123], v[160:163], v[184:187], v[120:123]
	v_mfma_f32_16x16x32_bf16 v[116:119], v[144:147], v[192:195], v[116:119]
	v_mfma_f32_16x16x32_bf16 v[108:111], v[160:163], v[192:195], v[108:111]
	v_mfma_f32_16x16x32_bf16 v[100:103], v[144:147], v[200:203], v[100:103]
	v_mfma_f32_16x16x32_bf16 v[92:95], v[160:163], v[200:203], v[92:95]
	v_mfma_f32_16x16x32_bf16 v[84:87], v[144:147], v[208:211], v[84:87]
	v_mfma_f32_16x16x32_bf16 v[76:79], v[160:163], v[208:211], v[76:79]
	v_mfma_f32_16x16x32_bf16 v[124:127], v[156:159], v[188:191], v[124:127]
	v_mfma_f32_16x16x32_bf16 v[120:123], v[164:167], v[188:191], v[120:123]
	v_mfma_f32_16x16x32_bf16 v[116:119], v[156:159], v[196:199], v[116:119]
	v_mfma_f32_16x16x32_bf16 v[108:111], v[164:167], v[196:199], v[108:111]
	v_mfma_f32_16x16x32_bf16 v[100:103], v[156:159], v[204:207], v[100:103]
	v_mfma_f32_16x16x32_bf16 v[92:95], v[164:167], v[204:207], v[92:95]
	v_mfma_f32_16x16x32_bf16 v[84:87], v[156:159], v[212:215], v[84:87]
	v_mfma_f32_16x16x32_bf16 v[76:79], v[164:167], v[212:215], v[76:79]
	s_setprio 0
	s_setprio 1
	v_mfma_f32_16x16x32_bf16 v[112:115], v[168:171], v[184:187], v[112:115]
	v_mfma_f32_16x16x32_bf16 v[104:107], v[176:179], v[184:187], v[104:107]
	v_mfma_f32_16x16x32_bf16 v[96:99], v[168:171], v[192:195], v[96:99]
	v_mfma_f32_16x16x32_bf16 v[88:91], v[176:179], v[192:195], v[88:91]
	v_mfma_f32_16x16x32_bf16 v[80:83], v[168:171], v[200:203], v[80:83]
	v_mfma_f32_16x16x32_bf16 v[72:75], v[176:179], v[200:203], v[72:75]
	v_mfma_f32_16x16x32_bf16 v[68:71], v[168:171], v[208:211], v[68:71]
	v_mfma_f32_16x16x32_bf16 v[64:67], v[176:179], v[208:211], v[64:67]
	v_mfma_f32_16x16x32_bf16 v[112:115], v[172:175], v[188:191], v[112:115]
	v_mfma_f32_16x16x32_bf16 v[104:107], v[180:183], v[188:191], v[104:107]
	v_mfma_f32_16x16x32_bf16 v[96:99], v[172:175], v[196:199], v[96:99]
	v_mfma_f32_16x16x32_bf16 v[88:91], v[180:183], v[196:199], v[88:91]
	v_mfma_f32_16x16x32_bf16 v[80:83], v[172:175], v[204:207], v[80:83]
	v_mfma_f32_16x16x32_bf16 v[72:75], v[180:183], v[204:207], v[72:75]
	v_mfma_f32_16x16x32_bf16 v[68:71], v[172:175], v[212:215], v[68:71]
	v_mfma_f32_16x16x32_bf16 v[64:67], v[180:183], v[212:215], v[64:67]
	s_setprio 0
	s_barrier
	s_add_i32 s33, s76, s54
	s_add_u32 s56, s44, s10
	s_addc_u32 s57, s45, s11
	s_mov_b32 m0, s33
	ds_read_b128 v[184:187], v154 offset:16384
	ds_read_b128 v[188:191], v154 offset:17408
	ds_read_b128 v[192:195], v154 offset:18432
	ds_read_b128 v[196:199], v154 offset:19456
	ds_read_b128 v[200:203], v154 offset:20480
	ds_read_b128 v[204:207], v154 offset:21504
	ds_read_b128 v[208:211], v154 offset:22528
	ds_read_b128 v[212:215], v154 offset:23552
	global_load_lds_dwordx4 v130, s[44:45]
	s_add_i32 m0, s33, 0x2000
	s_add_u32 s90, s44, 0x40000
	s_addc_u32 s91, s45, 0
	s_add_i32 s33, s77, s54
	global_load_lds_dwordx4 v134, s[44:45]
	s_mov_b32 m0, s33
	s_add_u32 s58, s46, s10
	s_addc_u32 s59, s47, s11
	global_load_lds_dwordx4 v130, s[90:91]
	s_add_i32 m0, s33, 0x2000
	s_nop 0
	global_load_lds_dwordx4 v134, s[90:91]
	s_mov_b32 m0, s41
	s_nop 0
	global_load_lds_dwordx4 v128, s[46:47]
	s_mov_b32 m0, s63
	s_nop 0
	global_load_lds_dwordx4 v132, s[46:47]
	s_waitcnt vmcnt(8)
	s_waitcnt lgkmcnt(0)
	s_barrier
	s_setprio 1
	s_waitcnt lgkmcnt(0)
	v_mfma_f32_16x16x32_bf16 v[60:63], v[144:147], v[184:187], v[60:63]
	v_mfma_f32_16x16x32_bf16 v[56:59], v[160:163], v[184:187], v[56:59]
	v_mfma_f32_16x16x32_bf16 v[52:55], v[144:147], v[192:195], v[52:55]
	v_mfma_f32_16x16x32_bf16 v[44:47], v[160:163], v[192:195], v[44:47]
	v_mfma_f32_16x16x32_bf16 v[36:39], v[144:147], v[200:203], v[36:39]
	v_mfma_f32_16x16x32_bf16 v[28:31], v[160:163], v[200:203], v[28:31]
	v_mfma_f32_16x16x32_bf16 v[20:23], v[144:147], v[208:211], v[20:23]
	v_mfma_f32_16x16x32_bf16 v[12:15], v[160:163], v[208:211], v[12:15]
	v_mfma_f32_16x16x32_bf16 v[60:63], v[156:159], v[188:191], v[60:63]
	v_mfma_f32_16x16x32_bf16 v[56:59], v[164:167], v[188:191], v[56:59]
	v_mfma_f32_16x16x32_bf16 v[52:55], v[156:159], v[196:199], v[52:55]
	v_mfma_f32_16x16x32_bf16 v[44:47], v[164:167], v[196:199], v[44:47]
	v_mfma_f32_16x16x32_bf16 v[36:39], v[156:159], v[204:207], v[36:39]
	v_mfma_f32_16x16x32_bf16 v[28:31], v[164:167], v[204:207], v[28:31]
	v_mfma_f32_16x16x32_bf16 v[20:23], v[156:159], v[212:215], v[20:23]
	v_mfma_f32_16x16x32_bf16 v[12:15], v[164:167], v[212:215], v[12:15]
	s_setprio 0
	s_setprio 1
	v_mfma_f32_16x16x32_bf16 v[48:51], v[168:171], v[184:187], v[48:51]
	v_mfma_f32_16x16x32_bf16 v[40:43], v[176:179], v[184:187], v[40:43]
	v_mfma_f32_16x16x32_bf16 v[32:35], v[168:171], v[192:195], v[32:35]
	v_mfma_f32_16x16x32_bf16 v[24:27], v[176:179], v[192:195], v[24:27]
	v_mfma_f32_16x16x32_bf16 v[16:19], v[168:171], v[200:203], v[16:19]
	v_mfma_f32_16x16x32_bf16 v[8:11], v[176:179], v[200:203], v[8:11]
	v_mfma_f32_16x16x32_bf16 v[4:7], v[168:171], v[208:211], v[4:7]
	v_mfma_f32_16x16x32_bf16 v[0:3], v[176:179], v[208:211], v[0:3]
	v_mfma_f32_16x16x32_bf16 v[48:51], v[172:175], v[188:191], v[48:51]
	v_mfma_f32_16x16x32_bf16 v[40:43], v[180:183], v[188:191], v[40:43]
	v_mfma_f32_16x16x32_bf16 v[32:35], v[172:175], v[196:199], v[32:35]
	v_mfma_f32_16x16x32_bf16 v[24:27], v[180:183], v[196:199], v[24:27]
	v_mfma_f32_16x16x32_bf16 v[16:19], v[172:175], v[204:207], v[16:19]
	v_mfma_f32_16x16x32_bf16 v[8:11], v[180:183], v[204:207], v[8:11]
	v_mfma_f32_16x16x32_bf16 v[4:7], v[172:175], v[212:215], v[4:7]
	v_mfma_f32_16x16x32_bf16 v[0:3], v[180:183], v[212:215], v[0:3]
	s_setprio 0
	s_barrier
; #define PG8_STAGE(bufoff, gbase, voff) do { _Pragma("unroll") for (int _i = 0; _i < 2; ++_i) \
;         __builtin_amdgcn_global_load_lds((const unsigned*)((const char*)(gbase) + (voff)[_i]), (PG8_LAS unsigned*)(lds + (bufoff) + ldsw + _i * 8192), 16, 0, 0); } while (0)
; #define PG8_LDA(dst, b, h) do { _Pragma("unroll") for (int m = 0; m < 4; ++m) _Pragma("unroll") for (int k = 0; k < 2; ++k) dst[m][k] = *(const PG8_LAS bf16x8*)(lds + PG8_SA(b, h) + aoff + m * 2048 + k * 1024); } while (0)
; #define PG8_LDB(dst, b, h) do { _Pragma("unroll") for (int n = 0; n < 2; ++n) _Pragma("unroll") for (int k = 0; k < 2; ++k) dst[n][k] = *(const PG8_LAS bf16x8*)(lds + PG8_SB(b, h) + boff + n * 2048 + k * 1024); } while (0)
; #define PG8_MMA(ai, bj, At, Bt) do { __builtin_amdgcn_s_setprio(1); _Pragma("unroll") for (int m = 0; m < 4; ++m) _Pragma("unroll") for (int n = 0; n < 2; ++n) _Pragma("unroll") for (int k = 0; k < 2; ++k) \
;         acc[ai][bj][m][n] = __builtin_amdgcn_mfma_f32_16x16x32_bf16(Bt[n][k], At[m][k], acc[ai][bj][m][n], 0, 0, 0); __builtin_amdgcn_s_setprio(0); } while (0)
; #define PG8_WAIT_V(n) asm volatile("s_waitcnt vmcnt(" #n ")" ::: "memory")
; #define PG8_WAIT_L(n) asm volatile("s_waitcnt lgkmcnt(" #n ")" ::: "memory")
; #define PG8_BAR __builtin_amdgcn_s_barrier()
; #define PG8_SCHED __builtin_amdgcn_sched_barrier(0)
; template <class Epi, class Sched, bool ALIGN_EPI = false, bool SP2 = false>
; __device__ __forceinline__ void gemm_phase(PG8_LAS unsigned char* lds, const Gemm g, const Sched& S, const Epi& E) {
;     ...
;         for (int t = 0; t < nt; t += 2) {
;     ...
;             PG8_LDB(B0, 1, 0); PG8_LDB(B1, 1, 1); PG8_SCHED; PG8_LDA(At, 1, 0); PG8_STAGE(PG8_SA(0, 1), a2 + hstep, voffA);
;             PG8_WAIT_V(8); PG8_WAIT_L(0); PG8_BAR; PG8_MMA(0, 0, At, B0); PG8_MMA(0, 1, At, B1); PG8_BAR; PG8_SCHED;
;             PG8_LDA(At, 1, 1); PG8_STAGE(PG8_SB(1, 0), b3, voffB); PG8_STAGE(PG8_SB(1, 1), b3 + hstep, voffB); PG8_STAGE(PG8_SA(1, 0), a3, voffA);
;             PG8_WAIT_V(8); PG8_WAIT_L(0); PG8_BAR; PG8_MMA(1, 0, At, B0); PG8_MMA(1, 1, At, B1); PG8_BAR; PG8_SCHED;
	s_add_i32 s33, 0, 0x18000
	v_add_u32_e32 v155, s33, v149
	s_add_i32 s34, 0, 0x1c000
	ds_read_b128 v[144:147], v155
	ds_read_b128 v[156:159], v155 offset:1024
	ds_read_b128 v[160:163], v155 offset:2048
	ds_read_b128 v[164:167], v155 offset:3072
	v_add_u32_e32 v155, s34, v149
	ds_read_b128 v[168:171], v155
	ds_read_b128 v[172:175], v155 offset:1024
	ds_read_b128 v[176:179], v155 offset:2048
	ds_read_b128 v[180:183], v155 offset:3072
	s_add_u32 s46, s46, 0x40000
	s_addc_u32 s47, s47, 0
	s_mov_b32 m0, s70
	ds_read_b128 v[184:187], v154 offset:32768
	ds_read_b128 v[188:191], v154 offset:33792
	ds_read_b128 v[192:195], v154 offset:34816
	ds_read_b128 v[196:199], v154 offset:35840
	ds_read_b128 v[200:203], v154 offset:36864
	ds_read_b128 v[204:207], v154 offset:37888
	ds_read_b128 v[208:211], v154 offset:38912
	ds_read_b128 v[212:215], v154 offset:39936
	global_load_lds_dwordx4 v128, s[46:47]
	s_mov_b32 m0, s71
	s_nop 0
	global_load_lds_dwordx4 v132, s[46:47]
	s_waitcnt vmcnt(8)
	s_waitcnt lgkmcnt(0)
	s_barrier
	s_setprio 1
	s_waitcnt lgkmcnt(0)
	v_mfma_f32_16x16x32_bf16 v[124:127], v[144:147], v[184:187], v[124:127]
	v_mfma_f32_16x16x32_bf16 v[120:123], v[160:163], v[184:187], v[120:123]
	v_mfma_f32_16x16x32_bf16 v[116:119], v[144:147], v[192:195], v[116:119]
	v_mfma_f32_16x16x32_bf16 v[108:111], v[160:163], v[192:195], v[108:111]
	v_mfma_f32_16x16x32_bf16 v[100:103], v[144:147], v[200:203], v[100:103]
	v_mfma_f32_16x16x32_bf16 v[92:95], v[160:163], v[200:203], v[92:95]
	v_mfma_f32_16x16x32_bf16 v[84:87], v[144:147], v[208:211], v[84:87]
	v_mfma_f32_16x16x32_bf16 v[76:79], v[160:163], v[208:211], v[76:79]
	v_mfma_f32_16x16x32_bf16 v[124:127], v[156:159], v[188:191], v[124:127]
	v_mfma_f32_16x16x32_bf16 v[120:123], v[164:167], v[188:191], v[120:123]
	v_mfma_f32_16x16x32_bf16 v[116:119], v[156:159], v[196:199], v[116:119]
	v_mfma_f32_16x16x32_bf16 v[108:111], v[164:167], v[196:199], v[108:111]
	v_mfma_f32_16x16x32_bf16 v[100:103], v[156:159], v[204:207], v[100:103]
	v_mfma_f32_16x16x32_bf16 v[92:95], v[164:167], v[204:207], v[92:95]
	v_mfma_f32_16x16x32_bf16 v[84:87], v[156:159], v[212:215], v[84:87]
	v_mfma_f32_16x16x32_bf16 v[76:79], v[164:167], v[212:215], v[76:79]
	s_setprio 0
	s_setprio 1
	v_mfma_f32_16x16x32_bf16 v[112:115], v[168:171], v[184:187], v[112:115]
	v_mfma_f32_16x16x32_bf16 v[104:107], v[176:179], v[184:187], v[104:107]
	v_mfma_f32_16x16x32_bf16 v[96:99], v[168:171], v[192:195], v[96:99]
	v_mfma_f32_16x16x32_bf16 v[88:91], v[176:179], v[192:195], v[88:91]
	v_mfma_f32_16x16x32_bf16 v[80:83], v[168:171], v[200:203], v[80:83]
	v_mfma_f32_16x16x32_bf16 v[72:75], v[176:179], v[200:203], v[72:75]
	v_mfma_f32_16x16x32_bf16 v[68:71], v[168:171], v[208:211], v[68:71]
	v_mfma_f32_16x16x32_bf16 v[64:67], v[176:179], v[208:211], v[64:67]
	v_mfma_f32_16x16x32_bf16 v[112:115], v[172:175], v[188:191], v[112:115]
	v_mfma_f32_16x16x32_bf16 v[104:107], v[180:183], v[188:191], v[104:107]
	v_mfma_f32_16x16x32_bf16 v[96:99], v[172:175], v[196:199], v[96:99]
	v_mfma_f32_16x16x32_bf16 v[88:91], v[180:183], v[196:199], v[88:91]
	v_mfma_f32_16x16x32_bf16 v[80:83], v[172:175], v[204:207], v[80:83]
	v_mfma_f32_16x16x32_bf16 v[72:75], v[180:183], v[204:207], v[72:75]
	v_mfma_f32_16x16x32_bf16 v[68:71], v[172:175], v[212:215], v[68:71]
	v_mfma_f32_16x16x32_bf16 v[64:67], v[180:183], v[212:215], v[64:67]
	s_setprio 0
	s_barrier
	s_add_i32 s33, s33, s54
	s_mov_b32 m0, s33
	ds_read_b128 v[184:187], v154 offset:49152
	ds_read_b128 v[188:191], v154 offset:50176
	ds_read_b128 v[192:195], v154 offset:51200
	ds_read_b128 v[196:199], v154 offset:52224
	ds_read_b128 v[200:203], v154 offset:53248
	ds_read_b128 v[204:207], v154 offset:54272
	ds_read_b128 v[208:211], v154 offset:55296
	ds_read_b128 v[212:215], v154 offset:56320
	global_load_lds_dwordx4 v130, s[56:57]
	s_add_i32 m0, s33, 0x2000
	s_add_u32 s44, s44, 0x40080
	s_addc_u32 s45, s45, 0
	s_add_i32 s33, s34, s54
	global_load_lds_dwordx4 v134, s[56:57]
	s_mov_b32 m0, s33
	s_nop 0
	global_load_lds_dwordx4 v130, s[44:45]
	s_add_i32 m0, s33, 0x2000
	s_nop 0
	global_load_lds_dwordx4 v134, s[44:45]
	s_mov_b32 m0, s74
	s_nop 0
	global_load_lds_dwordx4 v128, s[58:59]
	s_mov_b32 m0, s75
	s_nop 0
	global_load_lds_dwordx4 v132, s[58:59]
	s_waitcnt vmcnt(8)
	s_waitcnt lgkmcnt(0)
	s_barrier
	s_setprio 1
	s_waitcnt lgkmcnt(0)
	v_mfma_f32_16x16x32_bf16 v[60:63], v[144:147], v[184:187], v[60:63]
	v_mfma_f32_16x16x32_bf16 v[56:59], v[160:163], v[184:187], v[56:59]
	v_mfma_f32_16x16x32_bf16 v[52:55], v[144:147], v[192:195], v[52:55]
	v_mfma_f32_16x16x32_bf16 v[44:47], v[160:163], v[192:195], v[44:47]
	v_mfma_f32_16x16x32_bf16 v[36:39], v[144:147], v[200:203], v[36:39]
	v_mfma_f32_16x16x32_bf16 v[28:31], v[160:163], v[200:203], v[28:31]
	v_mfma_f32_16x16x32_bf16 v[20:23], v[144:147], v[208:211], v[20:23]
	v_mfma_f32_16x16x32_bf16 v[12:15], v[160:163], v[208:211], v[12:15]
	v_mfma_f32_16x16x32_bf16 v[60:63], v[156:159], v[188:191], v[60:63]
	v_mfma_f32_16x16x32_bf16 v[56:59], v[164:167], v[188:191], v[56:59]
	v_mfma_f32_16x16x32_bf16 v[52:55], v[156:159], v[196:199], v[52:55]
	v_mfma_f32_16x16x32_bf16 v[44:47], v[164:167], v[196:199], v[44:47]
	v_mfma_f32_16x16x32_bf16 v[36:39], v[156:159], v[204:207], v[36:39]
	v_mfma_f32_16x16x32_bf16 v[28:31], v[164:167], v[204:207], v[28:31]
	v_mfma_f32_16x16x32_bf16 v[20:23], v[156:159], v[212:215], v[20:23]
	v_mfma_f32_16x16x32_bf16 v[12:15], v[164:167], v[212:215], v[12:15]
	s_setprio 0
	s_setprio 1
	v_mfma_f32_16x16x32_bf16 v[48:51], v[168:171], v[184:187], v[48:51]
	v_mfma_f32_16x16x32_bf16 v[40:43], v[176:179], v[184:187], v[40:43]
	v_mfma_f32_16x16x32_bf16 v[32:35], v[168:171], v[192:195], v[32:35]
	v_mfma_f32_16x16x32_bf16 v[24:27], v[176:179], v[192:195], v[24:27]
	v_mfma_f32_16x16x32_bf16 v[16:19], v[168:171], v[200:203], v[16:19]
	v_mfma_f32_16x16x32_bf16 v[8:11], v[176:179], v[200:203], v[8:11]
	v_mfma_f32_16x16x32_bf16 v[4:7], v[168:171], v[208:211], v[4:7]
	v_mfma_f32_16x16x32_bf16 v[0:3], v[176:179], v[208:211], v[0:3]
	v_mfma_f32_16x16x32_bf16 v[48:51], v[172:175], v[188:191], v[48:51]
	v_mfma_f32_16x16x32_bf16 v[40:43], v[180:183], v[188:191], v[40:43]
	v_mfma_f32_16x16x32_bf16 v[32:35], v[172:175], v[196:199], v[32:35]
	v_mfma_f32_16x16x32_bf16 v[24:27], v[180:183], v[196:199], v[24:27]
	v_mfma_f32_16x16x32_bf16 v[16:19], v[172:175], v[204:207], v[16:19]
	v_mfma_f32_16x16x32_bf16 v[8:11], v[180:183], v[204:207], v[8:11]
	v_mfma_f32_16x16x32_bf16 v[4:7], v[172:175], v[212:215], v[4:7]
	v_mfma_f32_16x16x32_bf16 v[0:3], v[180:183], v[212:215], v[0:3]
	s_setprio 0
	s_barrier
	s_add_i32 s86, s86, 2
	s_add_u32 s42, s42, 0x100
	s_addc_u32 s43, s43, 0
	s_add_u32 s82, s82, 0x100
	s_addc_u32 s83, s83, 0
	s_cmp_gt_u32 s86, 13
	s_cbranch_scc0 .LBB0_381
	s_and_b64 vcc, exec, s[12:13]
	s_cbranch_vccz .LBB0_384
	s_barrier

; #define PG8_STAGE(bufoff, gbase, voff) do { _Pragma("unroll") for (int _i = 0; _i < 2; ++_i) \
;         __builtin_amdgcn_global_load_lds((const unsigned*)((const char*)(gbase) + (voff)[_i]), (PG8_LAS unsigned*)(lds + (bufoff) + ldsw + _i * 8192), 16, 0, 0); } while (0)
; #define PG8_LDA(dst, b, h) do { _Pragma("unroll") for (int m = 0; m < 4; ++m) _Pragma("unroll") for (int k = 0; k < 2; ++k) dst[m][k] = *(const PG8_LAS bf16x8*)(lds + PG8_SA(b, h) + aoff + m * 2048 + k * 1024); } while (0)
; #define PG8_LDB(dst, b, h) do { _Pragma("unroll") for (int n = 0; n < 2; ++n) _Pragma("unroll") for (int k = 0; k < 2; ++k) dst[n][k] = *(const PG8_LAS bf16x8*)(lds + PG8_SB(b, h) + boff + n * 2048 + k * 1024); } while (0)
; #define PG8_MMA(ai, bj, At, Bt) do { __builtin_amdgcn_s_setprio(1); _Pragma("unroll") for (int m = 0; m < 4; ++m) _Pragma("unroll") for (int n = 0; n < 2; ++n) _Pragma("unroll") for (int k = 0; k < 2; ++k) \
;         acc[ai][bj][m][n] = __builtin_amdgcn_mfma_f32_16x16x32_bf16(Bt[n][k], At[m][k], acc[ai][bj][m][n], 0, 0, 0); __builtin_amdgcn_s_setprio(0); } while (0)
; #define PG8_WAIT_V(n) asm volatile("s_waitcnt vmcnt(" #n ")" ::: "memory")
; #define PG8_WAIT_L(n) asm volatile("s_waitcnt lgkmcnt(" #n ")" ::: "memory")
; #define PG8_BAR __builtin_amdgcn_s_barrier()
; #define PG8_SCHED __builtin_amdgcn_sched_barrier(0)
; template <class Epi, class Sched, bool ALIGN_EPI = false, bool SP2 = false>
; __device__ __forceinline__ void gemm_phase(PG8_LAS unsigned char* lds, const Gemm g, const Sched& S, const Epi& E) {
;     ...
;             PG8_LDB(B0, 0, 0); PG8_LDB(B1, 0, 1); PG8_SCHED; PG8_LDA(At, 0, 0); PG8_STAGE(PG8_SA(1, 1), a1 + hstep, voffA);
;             PG8_WAIT_V(8); PG8_WAIT_L(0); PG8_BAR; PG8_MMA(0, 0, At, B0); PG8_MMA(0, 1, At, B1); PG8_BAR; PG8_SCHED;
;             PG8_LDA(At, 0, 1); PG8_STAGE(PG8_SB(0, 0), b2, voffB); PG8_STAGE(PG8_SB(0, 1), b2 + hstep, voffB); PG8_STAGE(PG8_SA(0, 0), a2, voffA);
;             PG8_WAIT_V(8); PG8_WAIT_L(0); PG8_BAR; PG8_MMA(1, 0, At, B0); PG8_MMA(1, 1, At, B1); PG8_BAR; PG8_SCHED;
.LBB0_590:
	ds_read_b128 v[128:131], v165
	ds_read_b128 v[132:135], v165 offset:1024
	ds_read_b128 v[154:157], v165 offset:2048
	ds_read_b128 v[158:161], v165 offset:3072
	ds_read_b128 v[168:171], v166
	ds_read_b128 v[172:175], v166 offset:1024
	ds_read_b128 v[176:179], v166 offset:2048
	ds_read_b128 v[180:183], v166 offset:3072
	s_add_u32 s33, s54, 0xfffc0080
	s_addc_u32 s34, s55, -1
	s_cmp_eq_u32 s92, 12
	s_cselect_b32 s59, s43, s34
	s_cselect_b32 s58, s86, s33
	s_cselect_b32 s57, s41, s91
	s_cselect_b32 s56, s87, s90
	s_add_i32 m0, s53, 0xc000
	ds_read_b128 v[184:187], v167
	ds_read_b128 v[188:191], v167 offset:1024
	ds_read_b128 v[192:195], v167 offset:2048
	ds_read_b128 v[196:199], v167 offset:3072
	ds_read_b128 v[200:203], v167 offset:4096
	ds_read_b128 v[204:207], v167 offset:5120
	ds_read_b128 v[208:211], v167 offset:6144
	ds_read_b128 v[212:215], v167 offset:7168
	global_load_lds_dwordx4 v144, s[54:55]
	s_add_i32 m0, s53, 0xe000
	s_nop 0
	global_load_lds_dwordx4 v146, s[54:55]
	s_waitcnt vmcnt(8)
	s_waitcnt lgkmcnt(0)
	s_barrier
	s_setprio 1
	s_waitcnt lgkmcnt(0)
	v_mfma_f32_16x16x32_bf16 v[124:127], v[128:131], v[184:187], v[124:127]
	v_mfma_f32_16x16x32_bf16 v[120:123], v[154:157], v[184:187], v[120:123]
	v_mfma_f32_16x16x32_bf16 v[116:119], v[128:131], v[192:195], v[116:119]
	v_mfma_f32_16x16x32_bf16 v[112:115], v[154:157], v[192:195], v[112:115]
	v_mfma_f32_16x16x32_bf16 v[108:111], v[128:131], v[200:203], v[108:111]
	v_mfma_f32_16x16x32_bf16 v[104:107], v[154:157], v[200:203], v[104:107]
	v_mfma_f32_16x16x32_bf16 v[100:103], v[128:131], v[208:211], v[100:103]
	v_mfma_f32_16x16x32_bf16 v[96:99], v[154:157], v[208:211], v[96:99]
	v_mfma_f32_16x16x32_bf16 v[124:127], v[132:135], v[188:191], v[124:127]
	v_mfma_f32_16x16x32_bf16 v[120:123], v[158:161], v[188:191], v[120:123]
	v_mfma_f32_16x16x32_bf16 v[116:119], v[132:135], v[196:199], v[116:119]
	v_mfma_f32_16x16x32_bf16 v[112:115], v[158:161], v[196:199], v[112:115]
	v_mfma_f32_16x16x32_bf16 v[108:111], v[132:135], v[204:207], v[108:111]
	v_mfma_f32_16x16x32_bf16 v[104:107], v[158:161], v[204:207], v[104:107]
	v_mfma_f32_16x16x32_bf16 v[100:103], v[132:135], v[212:215], v[100:103]
	v_mfma_f32_16x16x32_bf16 v[96:99], v[158:161], v[212:215], v[96:99]
	s_setprio 0
	s_setprio 1
	v_mfma_f32_16x16x32_bf16 v[68:71], v[168:171], v[184:187], v[68:71]
	v_mfma_f32_16x16x32_bf16 v[60:63], v[176:179], v[184:187], v[60:63]
	v_mfma_f32_16x16x32_bf16 v[52:55], v[168:171], v[192:195], v[52:55]
	v_mfma_f32_16x16x32_bf16 v[48:51], v[176:179], v[192:195], v[48:51]
	v_mfma_f32_16x16x32_bf16 v[44:47], v[168:171], v[200:203], v[44:47]
	v_mfma_f32_16x16x32_bf16 v[40:43], v[176:179], v[200:203], v[40:43]
	v_mfma_f32_16x16x32_bf16 v[36:39], v[168:171], v[208:211], v[36:39]
	v_mfma_f32_16x16x32_bf16 v[32:35], v[176:179], v[208:211], v[32:35]
	v_mfma_f32_16x16x32_bf16 v[68:71], v[172:175], v[188:191], v[68:71]
	v_mfma_f32_16x16x32_bf16 v[60:63], v[180:183], v[188:191], v[60:63]
	v_mfma_f32_16x16x32_bf16 v[52:55], v[172:175], v[196:199], v[52:55]
	v_mfma_f32_16x16x32_bf16 v[48:51], v[180:183], v[196:199], v[48:51]
	v_mfma_f32_16x16x32_bf16 v[44:47], v[172:175], v[204:207], v[44:47]
	v_mfma_f32_16x16x32_bf16 v[40:43], v[180:183], v[204:207], v[40:43]
	v_mfma_f32_16x16x32_bf16 v[36:39], v[172:175], v[212:215], v[36:39]
	v_mfma_f32_16x16x32_bf16 v[32:35], v[180:183], v[212:215], v[32:35]
	s_setprio 0
	s_barrier
	s_add_i32 s33, s81, s70
	s_add_u32 s64, s56, s10
	s_addc_u32 s65, s57, s11
	s_mov_b32 m0, s33
	ds_read_b128 v[184:187], v167 offset:16384
	ds_read_b128 v[188:191], v167 offset:17408
	ds_read_b128 v[192:195], v167 offset:18432
	ds_read_b128 v[196:199], v167 offset:19456
	ds_read_b128 v[200:203], v167 offset:20480
	ds_read_b128 v[204:207], v167 offset:21504
	ds_read_b128 v[208:211], v167 offset:22528
	ds_read_b128 v[212:215], v167 offset:23552
	global_load_lds_dwordx4 v138, s[56:57]
	s_add_i32 m0, s33, 0x2000
	s_add_u32 s94, s56, 0x40000
	s_addc_u32 s95, s57, 0
	s_add_i32 s33, s82, s70
	global_load_lds_dwordx4 v142, s[56:57]
	s_mov_b32 m0, s33
	s_add_u32 s84, s58, s10
	s_addc_u32 s85, s59, s11
	global_load_lds_dwordx4 v138, s[94:95]
	s_add_i32 m0, s33, 0x2000
	s_nop 0
	global_load_lds_dwordx4 v142, s[94:95]
	s_mov_b32 m0, s53
	s_nop 0
	global_load_lds_dwordx4 v136, s[58:59]
	s_mov_b32 m0, s72
	s_nop 0
	global_load_lds_dwordx4 v140, s[58:59]
	s_waitcnt vmcnt(8)
	s_waitcnt lgkmcnt(0)
	s_barrier
	s_setprio 1
	s_waitcnt lgkmcnt(0)
	v_mfma_f32_16x16x32_bf16 v[92:95], v[128:131], v[184:187], v[92:95]
	v_mfma_f32_16x16x32_bf16 v[88:91], v[154:157], v[184:187], v[88:91]
	v_mfma_f32_16x16x32_bf16 v[84:87], v[128:131], v[192:195], v[84:87]
	v_mfma_f32_16x16x32_bf16 v[80:83], v[154:157], v[192:195], v[80:83]
	v_mfma_f32_16x16x32_bf16 v[76:79], v[128:131], v[200:203], v[76:79]
	v_mfma_f32_16x16x32_bf16 v[72:75], v[154:157], v[200:203], v[72:75]
	v_mfma_f32_16x16x32_bf16 v[64:67], v[128:131], v[208:211], v[64:67]
	v_mfma_f32_16x16x32_bf16 v[56:59], v[154:157], v[208:211], v[56:59]
	v_mfma_f32_16x16x32_bf16 v[92:95], v[132:135], v[188:191], v[92:95]
	v_mfma_f32_16x16x32_bf16 v[88:91], v[158:161], v[188:191], v[88:91]
	v_mfma_f32_16x16x32_bf16 v[84:87], v[132:135], v[196:199], v[84:87]
	v_mfma_f32_16x16x32_bf16 v[80:83], v[158:161], v[196:199], v[80:83]
	v_mfma_f32_16x16x32_bf16 v[76:79], v[132:135], v[204:207], v[76:79]
	v_mfma_f32_16x16x32_bf16 v[72:75], v[158:161], v[204:207], v[72:75]
	v_mfma_f32_16x16x32_bf16 v[64:67], v[132:135], v[212:215], v[64:67]
	v_mfma_f32_16x16x32_bf16 v[56:59], v[158:161], v[212:215], v[56:59]
	s_setprio 0
	s_setprio 1
	v_mfma_f32_16x16x32_bf16 v[28:31], v[168:171], v[184:187], v[28:31]
	v_mfma_f32_16x16x32_bf16 v[24:27], v[176:179], v[184:187], v[24:27]
	v_mfma_f32_16x16x32_bf16 v[20:23], v[168:171], v[192:195], v[20:23]
	v_mfma_f32_16x16x32_bf16 v[16:19], v[176:179], v[192:195], v[16:19]
	v_mfma_f32_16x16x32_bf16 v[12:15], v[168:171], v[200:203], v[12:15]
	v_mfma_f32_16x16x32_bf16 v[8:11], v[176:179], v[200:203], v[8:11]
	v_mfma_f32_16x16x32_bf16 v[4:7], v[168:171], v[208:211], v[4:7]
	v_mfma_f32_16x16x32_bf16 v[0:3], v[176:179], v[208:211], v[0:3]
	v_mfma_f32_16x16x32_bf16 v[28:31], v[172:175], v[188:191], v[28:31]
	v_mfma_f32_16x16x32_bf16 v[24:27], v[180:183], v[188:191], v[24:27]
	v_mfma_f32_16x16x32_bf16 v[20:23], v[172:175], v[196:199], v[20:23]
	v_mfma_f32_16x16x32_bf16 v[16:19], v[180:183], v[196:199], v[16:19]
	v_mfma_f32_16x16x32_bf16 v[12:15], v[172:175], v[204:207], v[12:15]
	v_mfma_f32_16x16x32_bf16 v[8:11], v[180:183], v[204:207], v[8:11]
	v_mfma_f32_16x16x32_bf16 v[4:7], v[172:175], v[212:215], v[4:7]
	v_mfma_f32_16x16x32_bf16 v[0:3], v[180:183], v[212:215], v[0:3]
	s_setprio 0
	s_barrier
; #define PG8_STAGE(bufoff, gbase, voff) do { _Pragma("unroll") for (int _i = 0; _i < 2; ++_i) \
;         __builtin_amdgcn_global_load_lds((const unsigned*)((const char*)(gbase) + (voff)[_i]), (PG8_LAS unsigned*)(lds + (bufoff) + ldsw + _i * 8192), 16, 0, 0); } while (0)
; #define PG8_LDA(dst, b, h) do { _Pragma("unroll") for (int m = 0; m < 4; ++m) _Pragma("unroll") for (int k = 0; k < 2; ++k) dst[m][k] = *(const PG8_LAS bf16x8*)(lds + PG8_SA(b, h) + aoff + m * 2048 + k * 1024); } while (0)
; #define PG8_LDB(dst, b, h) do { _Pragma("unroll") for (int n = 0; n < 2; ++n) _Pragma("unroll") for (int k = 0; k < 2; ++k) dst[n][k] = *(const PG8_LAS bf16x8*)(lds + PG8_SB(b, h) + boff + n * 2048 + k * 1024); } while (0)
; template <class Epi, class Sched, bool ALIGN_EPI = false, bool SP2 = false>
; __device__ __forceinline__ void gemm_phase(PG8_LAS unsigned char* lds, const Gemm g, const Sched& S, const Epi& E) {
;     ...
;         for (int t = 0; t < nt; t += 2) {
;             const bool last = (t == nt - 2);
;             const char* a1 = cA + (size_t)(t + 1) * kstep;
;             const char* a2 = last ? nA : cA + (size_t)(t + 2) * kstep; const char* b2 = last ? nB : cB + (size_t)(t + 2) * kstep;
;             const char* a3 = a2 + kstep; const char* b3 = b2 + kstep;
;             if (last && has_next) S.a_ready(nxt);
;             if constexpr (SP2) {
;             PG8_LDB(B0, 0, 0); PG8_LDB(B1, 0, 1); PG8_SCHED; PG8_LDA(At, 0, 0); PG8_STAGE(PG8_SA(1, 1), a1 + hstep, voffA);
;             PG8_WAIT_V(8); PG8_WAIT_L(0); PG8_BAR; PG8_MMA(0, 0, At, B0); PG8_MMA(0, 1, At, B1); PG8_BAR; PG8_SCHED;
;             PG8_LDA(At, 0, 1); PG8_STAGE(PG8_SB(0, 0), b2, voffB); PG8_STAGE(PG8_SB(0, 1), b2 + hstep, voffB); PG8_STAGE(PG8_SA(0, 0), a2, voffA);
;             PG8_WAIT_V(8); PG8_WAIT_L(0); PG8_BAR; PG8_MMA(1, 0, At, B0); PG8_MMA(1, 1, At, B1); PG8_BAR; PG8_SCHED;
;             PG8_LDB(B0, 1, 0); PG8_LDB(B1, 1, 1); PG8_SCHED; PG8_LDA(At, 1, 0); PG8_STAGE(PG8_SA(0, 1), a2 + hstep, voffA);
;             PG8_WAIT_V(8); PG8_WAIT_L(0); PG8_BAR; PG8_MMA(0, 0, At, B0); PG8_MMA(0, 1, At, B1); PG8_BAR; PG8_SCHED;
;             PG8_LDA(At, 1, 1); PG8_STAGE(PG8_SB(1, 0), b3, voffB); PG8_STAGE(PG8_SB(1, 1), b3 + hstep, voffB); PG8_STAGE(PG8_SA(1, 0), a3, voffA);
;             PG8_WAIT_V(8); PG8_WAIT_L(0); PG8_BAR; PG8_MMA(1, 0, At, B0); PG8_MMA(1, 1, At, B1); PG8_BAR; PG8_SCHED;
	s_add_i32 s33, 0, 0x18000
	v_add_u32_e32 v153, s33, v163
	s_add_i32 s34, 0, 0x1c000
	ds_read_b128 v[128:131], v153
	ds_read_b128 v[132:135], v153 offset:1024
	ds_read_b128 v[154:157], v153 offset:2048
	ds_read_b128 v[158:161], v153 offset:3072
	v_add_u32_e32 v153, s34, v163
	ds_read_b128 v[168:171], v153
	ds_read_b128 v[172:175], v153 offset:1024
	ds_read_b128 v[176:179], v153 offset:2048
	ds_read_b128 v[180:183], v153 offset:3072
	s_add_u32 s58, s58, 0x40000
	s_addc_u32 s59, s59, 0
	s_mov_b32 m0, s73
	ds_read_b128 v[184:187], v167 offset:32768
	ds_read_b128 v[188:191], v167 offset:33792
	ds_read_b128 v[192:195], v167 offset:34816
	ds_read_b128 v[196:199], v167 offset:35840
	ds_read_b128 v[200:203], v167 offset:36864
	ds_read_b128 v[204:207], v167 offset:37888
	ds_read_b128 v[208:211], v167 offset:38912
	ds_read_b128 v[212:215], v167 offset:39936
	global_load_lds_dwordx4 v136, s[58:59]
	s_mov_b32 m0, s74
	s_nop 0
	global_load_lds_dwordx4 v140, s[58:59]
	s_waitcnt vmcnt(8)
	s_waitcnt lgkmcnt(0)
	s_barrier
	s_setprio 1
	s_waitcnt lgkmcnt(0)
	v_mfma_f32_16x16x32_bf16 v[124:127], v[128:131], v[184:187], v[124:127]
	v_mfma_f32_16x16x32_bf16 v[120:123], v[154:157], v[184:187], v[120:123]
	v_mfma_f32_16x16x32_bf16 v[116:119], v[128:131], v[192:195], v[116:119]
	v_mfma_f32_16x16x32_bf16 v[112:115], v[154:157], v[192:195], v[112:115]
	v_mfma_f32_16x16x32_bf16 v[108:111], v[128:131], v[200:203], v[108:111]
	v_mfma_f32_16x16x32_bf16 v[104:107], v[154:157], v[200:203], v[104:107]
	v_mfma_f32_16x16x32_bf16 v[100:103], v[128:131], v[208:211], v[100:103]
	v_mfma_f32_16x16x32_bf16 v[96:99], v[154:157], v[208:211], v[96:99]
	v_mfma_f32_16x16x32_bf16 v[124:127], v[132:135], v[188:191], v[124:127]
	v_mfma_f32_16x16x32_bf16 v[120:123], v[158:161], v[188:191], v[120:123]
	v_mfma_f32_16x16x32_bf16 v[116:119], v[132:135], v[196:199], v[116:119]
	v_mfma_f32_16x16x32_bf16 v[112:115], v[158:161], v[196:199], v[112:115]
	v_mfma_f32_16x16x32_bf16 v[108:111], v[132:135], v[204:207], v[108:111]
	v_mfma_f32_16x16x32_bf16 v[104:107], v[158:161], v[204:207], v[104:107]
	v_mfma_f32_16x16x32_bf16 v[100:103], v[132:135], v[212:215], v[100:103]
	v_mfma_f32_16x16x32_bf16 v[96:99], v[158:161], v[212:215], v[96:99]
	s_setprio 0
	s_setprio 1
	v_mfma_f32_16x16x32_bf16 v[68:71], v[168:171], v[184:187], v[68:71]
	v_mfma_f32_16x16x32_bf16 v[60:63], v[176:179], v[184:187], v[60:63]
	v_mfma_f32_16x16x32_bf16 v[52:55], v[168:171], v[192:195], v[52:55]
	v_mfma_f32_16x16x32_bf16 v[48:51], v[176:179], v[192:195], v[48:51]
	v_mfma_f32_16x16x32_bf16 v[44:47], v[168:171], v[200:203], v[44:47]
	v_mfma_f32_16x16x32_bf16 v[40:43], v[176:179], v[200:203], v[40:43]
	v_mfma_f32_16x16x32_bf16 v[36:39], v[168:171], v[208:211], v[36:39]
	v_mfma_f32_16x16x32_bf16 v[32:35], v[176:179], v[208:211], v[32:35]
	v_mfma_f32_16x16x32_bf16 v[68:71], v[172:175], v[188:191], v[68:71]
	v_mfma_f32_16x16x32_bf16 v[60:63], v[180:183], v[188:191], v[60:63]
	v_mfma_f32_16x16x32_bf16 v[52:55], v[172:175], v[196:199], v[52:55]
	v_mfma_f32_16x16x32_bf16 v[48:51], v[180:183], v[196:199], v[48:51]
	v_mfma_f32_16x16x32_bf16 v[44:47], v[172:175], v[204:207], v[44:47]
	v_mfma_f32_16x16x32_bf16 v[40:43], v[180:183], v[204:207], v[40:43]
	v_mfma_f32_16x16x32_bf16 v[36:39], v[172:175], v[212:215], v[36:39]
	v_mfma_f32_16x16x32_bf16 v[32:35], v[180:183], v[212:215], v[32:35]
	s_setprio 0
	s_barrier
	s_add_i32 s33, s33, s70
	s_mov_b32 m0, s33
	ds_read_b128 v[184:187], v167 offset:49152
	ds_read_b128 v[188:191], v167 offset:50176
	ds_read_b128 v[192:195], v167 offset:51200
	ds_read_b128 v[196:199], v167 offset:52224
	ds_read_b128 v[200:203], v167 offset:53248
	ds_read_b128 v[204:207], v167 offset:54272
	ds_read_b128 v[208:211], v167 offset:55296
	ds_read_b128 v[212:215], v167 offset:56320
	global_load_lds_dwordx4 v138, s[64:65]
	s_add_i32 m0, s33, 0x2000
	s_add_u32 s56, s56, 0x40080
	s_addc_u32 s57, s57, 0
	s_add_i32 s33, s34, s70
	global_load_lds_dwordx4 v142, s[64:65]
	s_mov_b32 m0, s33
	s_nop 0
	global_load_lds_dwordx4 v138, s[56:57]
	s_add_i32 m0, s33, 0x2000
	s_nop 0
	global_load_lds_dwordx4 v142, s[56:57]
	s_mov_b32 m0, s79
	s_nop 0
	global_load_lds_dwordx4 v136, s[84:85]
	s_mov_b32 m0, s80
	s_nop 0
	global_load_lds_dwordx4 v140, s[84:85]
	s_waitcnt vmcnt(8)
	s_waitcnt lgkmcnt(0)
	s_barrier
	s_setprio 1
	s_waitcnt lgkmcnt(0)
	v_mfma_f32_16x16x32_bf16 v[92:95], v[128:131], v[184:187], v[92:95]
	v_mfma_f32_16x16x32_bf16 v[88:91], v[154:157], v[184:187], v[88:91]
	v_mfma_f32_16x16x32_bf16 v[84:87], v[128:131], v[192:195], v[84:87]
	v_mfma_f32_16x16x32_bf16 v[80:83], v[154:157], v[192:195], v[80:83]
	v_mfma_f32_16x16x32_bf16 v[76:79], v[128:131], v[200:203], v[76:79]
	v_mfma_f32_16x16x32_bf16 v[72:75], v[154:157], v[200:203], v[72:75]
	v_mfma_f32_16x16x32_bf16 v[64:67], v[128:131], v[208:211], v[64:67]
	v_mfma_f32_16x16x32_bf16 v[56:59], v[154:157], v[208:211], v[56:59]
	v_mfma_f32_16x16x32_bf16 v[92:95], v[132:135], v[188:191], v[92:95]
	v_mfma_f32_16x16x32_bf16 v[88:91], v[158:161], v[188:191], v[88:91]
	v_mfma_f32_16x16x32_bf16 v[84:87], v[132:135], v[196:199], v[84:87]
	v_mfma_f32_16x16x32_bf16 v[80:83], v[158:161], v[196:199], v[80:83]
	v_mfma_f32_16x16x32_bf16 v[76:79], v[132:135], v[204:207], v[76:79]
	v_mfma_f32_16x16x32_bf16 v[72:75], v[158:161], v[204:207], v[72:75]
	v_mfma_f32_16x16x32_bf16 v[64:67], v[132:135], v[212:215], v[64:67]
	v_mfma_f32_16x16x32_bf16 v[56:59], v[158:161], v[212:215], v[56:59]
	s_setprio 0
	s_setprio 1
	v_mfma_f32_16x16x32_bf16 v[28:31], v[168:171], v[184:187], v[28:31]
	v_mfma_f32_16x16x32_bf16 v[24:27], v[176:179], v[184:187], v[24:27]
	v_mfma_f32_16x16x32_bf16 v[20:23], v[168:171], v[192:195], v[20:23]
	v_mfma_f32_16x16x32_bf16 v[16:19], v[176:179], v[192:195], v[16:19]
	v_mfma_f32_16x16x32_bf16 v[12:15], v[168:171], v[200:203], v[12:15]
	v_mfma_f32_16x16x32_bf16 v[8:11], v[176:179], v[200:203], v[8:11]
	v_mfma_f32_16x16x32_bf16 v[4:7], v[168:171], v[208:211], v[4:7]
	v_mfma_f32_16x16x32_bf16 v[0:3], v[176:179], v[208:211], v[0:3]
	v_mfma_f32_16x16x32_bf16 v[28:31], v[172:175], v[188:191], v[28:31]
	v_mfma_f32_16x16x32_bf16 v[24:27], v[180:183], v[188:191], v[24:27]
	v_mfma_f32_16x16x32_bf16 v[20:23], v[172:175], v[196:199], v[20:23]
	v_mfma_f32_16x16x32_bf16 v[16:19], v[180:183], v[196:199], v[16:19]
	v_mfma_f32_16x16x32_bf16 v[12:15], v[172:175], v[204:207], v[12:15]
	v_mfma_f32_16x16x32_bf16 v[8:11], v[180:183], v[204:207], v[8:11]
	v_mfma_f32_16x16x32_bf16 v[4:7], v[172:175], v[212:215], v[4:7]
	v_mfma_f32_16x16x32_bf16 v[0:3], v[180:183], v[212:215], v[0:3]
	s_setprio 0
	s_barrier
	s_add_i32 s92, s92, 2
	s_add_u32 s54, s54, 0x100
	s_addc_u32 s55, s55, 0
	s_add_u32 s90, s90, 0x100
	s_addc_u32 s91, s91, 0
	s_cmp_gt_u32 s92, 13
	s_cbranch_scc0 .LBB0_590
	s_and_b64 vcc, exec, s[12:13]
	s_cbranch_vccz .LBB0_593
	s_barrier

; #define PG8_STAGE(bufoff, gbase, voff) do { _Pragma("unroll") for (int _i = 0; _i < 2; ++_i) \
;         __builtin_amdgcn_global_load_lds((const unsigned*)((const char*)(gbase) + (voff)[_i]), (PG8_LAS unsigned*)(lds + (bufoff) + ldsw + _i * 8192), 16, 0, 0); } while (0)
; #define PG8_LDA(dst, b, h) do { _Pragma("unroll") for (int m = 0; m < 4; ++m) _Pragma("unroll") for (int k = 0; k < 2; ++k) dst[m][k] = *(const PG8_LAS bf16x8*)(lds + PG8_SA(b, h) + aoff + m * 2048 + k * 1024); } while (0)
; #define PG8_LDB(dst, b, h) do { _Pragma("unroll") for (int n = 0; n < 2; ++n) _Pragma("unroll") for (int k = 0; k < 2; ++k) dst[n][k] = *(const PG8_LAS bf16x8*)(lds + PG8_SB(b, h) + boff + n * 2048 + k * 1024); } while (0)
; #define PG8_MMA(ai, bj, At, Bt) do { __builtin_amdgcn_s_setprio(1); _Pragma("unroll") for (int m = 0; m < 4; ++m) _Pragma("unroll") for (int n = 0; n < 2; ++n) _Pragma("unroll") for (int k = 0; k < 2; ++k) \
;         acc[ai][bj][m][n] = __builtin_amdgcn_mfma_f32_16x16x32_bf16(Bt[n][k], At[m][k], acc[ai][bj][m][n], 0, 0, 0); __builtin_amdgcn_s_setprio(0); } while (0)
; #define PG8_WAIT_V(n) asm volatile("s_waitcnt vmcnt(" #n ")" ::: "memory")
; #define PG8_WAIT_L(n) asm volatile("s_waitcnt lgkmcnt(" #n ")" ::: "memory")
; template <class Epi, class Sched, bool ALIGN_EPI = false, bool SP2 = false>
; __device__ __forceinline__ void gemm_phase(PG8_LAS unsigned char* lds, const Gemm g, const Sched& S, const Epi& E) {
;     ...
;             const bool last = (t == nt - 2);
;             const char* a1 = cA + (size_t)(t + 1) * kstep;
;             const char* a2 = last ? nA : cA + (size_t)(t + 2) * kstep; const char* b2 = last ? nB : cB + (size_t)(t + 2) * kstep;
;             const char* a3 = a2 + kstep; const char* b3 = b2 + kstep;
;             if (last && has_next) S.a_ready(nxt);
;             if constexpr (SP2) {
;             PG8_LDB(B0, 0, 0); PG8_LDB(B1, 0, 1); PG8_SCHED; PG8_LDA(At, 0, 0); PG8_STAGE(PG8_SA(1, 1), a1 + hstep, voffA);
;             PG8_WAIT_V(8); PG8_WAIT_L(0); PG8_BAR; PG8_MMA(0, 0, At, B0); PG8_MMA(0, 1, At, B1); PG8_BAR; PG8_SCHED;
;             PG8_LDA(At, 0, 1); PG8_STAGE(PG8_SB(0, 0), b2, voffB); PG8_STAGE(PG8_SB(0, 1), b2 + hstep, voffB); PG8_STAGE(PG8_SA(0, 0), a2, voffA);
;             PG8_WAIT_V(8); PG8_WAIT_L(0); PG8_BAR; PG8_MMA(1, 0, At, B0); PG8_MMA(1, 1, At, B1); PG8_BAR; PG8_SCHED;
.LBB0_789:
	ds_read_b128 v[128:131], v203
	ds_read_b128 v[132:135], v203 offset:1024
	ds_read_b128 v[136:139], v203 offset:2048
	ds_read_b128 v[140:143], v203 offset:3072
	ds_read_b128 v[144:147], v204
	ds_read_b128 v[148:151], v204 offset:1024
	ds_read_b128 v[170:173], v204 offset:2048
	ds_read_b128 v[174:177], v204 offset:3072
	s_add_u32 s33, s42, 0xfff50080
	s_addc_u32 s34, s43, -1
	s_cmp_eq_u32 s90, 40
	s_cselect_b32 s47, s5, s34
	s_cselect_b32 s46, s4, s33
	s_cselect_b32 s45, s41, s87
	s_cselect_b32 s44, s40, s86
	s_add_i32 m0, s58, 0xc000
	ds_read_b128 v[178:181], v205
	ds_read_b128 v[182:185], v205 offset:1024
	ds_read_b128 v[186:189], v205 offset:2048
	ds_read_b128 v[190:193], v205 offset:3072
	ds_read_b128 v[194:197], v205 offset:4096
	ds_read_b128 v[206:209], v205 offset:5120
	ds_read_b128 v[210:213], v205 offset:6144
	ds_read_b128 v[214:217], v205 offset:7168
	global_load_lds_dwordx4 v162, s[42:43]
	s_add_i32 m0, s58, 0xe000
	s_nop 0
	global_load_lds_dwordx4 v164, s[42:43]
	s_waitcnt vmcnt(8)
	s_waitcnt lgkmcnt(0)
	s_barrier
	s_setprio 1
	s_waitcnt lgkmcnt(0)
	v_mfma_f32_16x16x32_bf16 v[124:127], v[128:131], v[178:181], v[124:127]
	v_mfma_f32_16x16x32_bf16 v[120:123], v[136:139], v[178:181], v[120:123]
	v_mfma_f32_16x16x32_bf16 v[116:119], v[128:131], v[186:189], v[116:119]
	v_mfma_f32_16x16x32_bf16 v[112:115], v[136:139], v[186:189], v[112:115]
	v_mfma_f32_16x16x32_bf16 v[108:111], v[128:131], v[194:197], v[108:111]
	v_mfma_f32_16x16x32_bf16 v[104:107], v[136:139], v[194:197], v[104:107]
	v_mfma_f32_16x16x32_bf16 v[100:103], v[128:131], v[210:213], v[100:103]
	v_mfma_f32_16x16x32_bf16 v[96:99], v[136:139], v[210:213], v[96:99]
	v_mfma_f32_16x16x32_bf16 v[124:127], v[132:135], v[182:185], v[124:127]
	v_mfma_f32_16x16x32_bf16 v[120:123], v[140:143], v[182:185], v[120:123]
	v_mfma_f32_16x16x32_bf16 v[116:119], v[132:135], v[190:193], v[116:119]
	v_mfma_f32_16x16x32_bf16 v[112:115], v[140:143], v[190:193], v[112:115]
	v_mfma_f32_16x16x32_bf16 v[108:111], v[132:135], v[206:209], v[108:111]
	v_mfma_f32_16x16x32_bf16 v[104:107], v[140:143], v[206:209], v[104:107]
	v_mfma_f32_16x16x32_bf16 v[100:103], v[132:135], v[214:217], v[100:103]
	v_mfma_f32_16x16x32_bf16 v[96:99], v[140:143], v[214:217], v[96:99]
	s_setprio 0
	s_setprio 1
	v_mfma_f32_16x16x32_bf16 v[68:71], v[144:147], v[178:181], v[68:71]
	v_mfma_f32_16x16x32_bf16 v[64:67], v[170:173], v[178:181], v[64:67]
	v_mfma_f32_16x16x32_bf16 v[60:63], v[144:147], v[186:189], v[60:63]
	v_mfma_f32_16x16x32_bf16 v[52:55], v[170:173], v[186:189], v[52:55]
	v_mfma_f32_16x16x32_bf16 v[44:47], v[144:147], v[194:197], v[44:47]
	v_mfma_f32_16x16x32_bf16 v[40:43], v[170:173], v[194:197], v[40:43]
	v_mfma_f32_16x16x32_bf16 v[36:39], v[144:147], v[210:213], v[36:39]
	v_mfma_f32_16x16x32_bf16 v[32:35], v[170:173], v[210:213], v[32:35]
	v_mfma_f32_16x16x32_bf16 v[68:71], v[148:151], v[182:185], v[68:71]
	v_mfma_f32_16x16x32_bf16 v[64:67], v[174:177], v[182:185], v[64:67]
	v_mfma_f32_16x16x32_bf16 v[60:63], v[148:151], v[190:193], v[60:63]
	v_mfma_f32_16x16x32_bf16 v[52:55], v[174:177], v[190:193], v[52:55]
	v_mfma_f32_16x16x32_bf16 v[44:47], v[148:151], v[206:209], v[44:47]
	v_mfma_f32_16x16x32_bf16 v[40:43], v[174:177], v[206:209], v[40:43]
	v_mfma_f32_16x16x32_bf16 v[36:39], v[148:151], v[214:217], v[36:39]
	v_mfma_f32_16x16x32_bf16 v[32:35], v[174:177], v[214:217], v[32:35]
	s_setprio 0
	s_barrier
	s_add_i32 s33, s74, s56
	s_add_u32 s64, s44, s12
	s_addc_u32 s65, s45, s13
	s_mov_b32 m0, s33
	ds_read_b128 v[178:181], v205 offset:16384
	ds_read_b128 v[182:185], v205 offset:17408
	ds_read_b128 v[186:189], v205 offset:18432
	ds_read_b128 v[190:193], v205 offset:19456
	ds_read_b128 v[194:197], v205 offset:20480
	ds_read_b128 v[206:209], v205 offset:21504
	ds_read_b128 v[210:213], v205 offset:22528
	ds_read_b128 v[214:217], v205 offset:23552
	global_load_lds_dwordx4 v156, s[44:45]
	s_add_i32 m0, s33, 0x2000
	s_add_u32 s92, s44, 0xb0000
	s_addc_u32 s93, s45, 0
	s_add_i32 s33, s75, s56
	global_load_lds_dwordx4 v160, s[44:45]
	s_mov_b32 m0, s33
	s_add_u32 s84, s46, s12
	s_addc_u32 s85, s47, s13
	global_load_lds_dwordx4 v156, s[92:93]
	s_add_i32 m0, s33, 0x2000
	s_nop 0
	global_load_lds_dwordx4 v160, s[92:93]
	s_mov_b32 m0, s58
	s_nop 0
	global_load_lds_dwordx4 v154, s[46:47]
	s_mov_b32 m0, s59
	s_nop 0
	global_load_lds_dwordx4 v158, s[46:47]
	s_waitcnt vmcnt(8)
	s_waitcnt lgkmcnt(0)
	s_barrier
	s_setprio 1
	s_waitcnt lgkmcnt(0)
	v_mfma_f32_16x16x32_bf16 v[92:95], v[128:131], v[178:181], v[92:95]
	v_mfma_f32_16x16x32_bf16 v[88:91], v[136:139], v[178:181], v[88:91]
	v_mfma_f32_16x16x32_bf16 v[84:87], v[128:131], v[186:189], v[84:87]
	v_mfma_f32_16x16x32_bf16 v[80:83], v[136:139], v[186:189], v[80:83]
	v_mfma_f32_16x16x32_bf16 v[76:79], v[128:131], v[194:197], v[76:79]
	v_mfma_f32_16x16x32_bf16 v[72:75], v[136:139], v[194:197], v[72:75]
	v_mfma_f32_16x16x32_bf16 v[56:59], v[128:131], v[210:213], v[56:59]
	v_mfma_f32_16x16x32_bf16 v[48:51], v[136:139], v[210:213], v[48:51]
	v_mfma_f32_16x16x32_bf16 v[92:95], v[132:135], v[182:185], v[92:95]
	v_mfma_f32_16x16x32_bf16 v[88:91], v[140:143], v[182:185], v[88:91]
	v_mfma_f32_16x16x32_bf16 v[84:87], v[132:135], v[190:193], v[84:87]
	v_mfma_f32_16x16x32_bf16 v[80:83], v[140:143], v[190:193], v[80:83]
	v_mfma_f32_16x16x32_bf16 v[76:79], v[132:135], v[206:209], v[76:79]
	v_mfma_f32_16x16x32_bf16 v[72:75], v[140:143], v[206:209], v[72:75]
	v_mfma_f32_16x16x32_bf16 v[56:59], v[132:135], v[214:217], v[56:59]
	v_mfma_f32_16x16x32_bf16 v[48:51], v[140:143], v[214:217], v[48:51]
	s_setprio 0
	s_setprio 1
	v_mfma_f32_16x16x32_bf16 v[28:31], v[144:147], v[178:181], v[28:31]
	v_mfma_f32_16x16x32_bf16 v[24:27], v[170:173], v[178:181], v[24:27]
	v_mfma_f32_16x16x32_bf16 v[20:23], v[144:147], v[186:189], v[20:23]
	v_mfma_f32_16x16x32_bf16 v[16:19], v[170:173], v[186:189], v[16:19]
	v_mfma_f32_16x16x32_bf16 v[12:15], v[144:147], v[194:197], v[12:15]
	v_mfma_f32_16x16x32_bf16 v[8:11], v[170:173], v[194:197], v[8:11]
	v_mfma_f32_16x16x32_bf16 v[4:7], v[144:147], v[210:213], v[4:7]
	v_mfma_f32_16x16x32_bf16 v[0:3], v[170:173], v[210:213], v[0:3]
	v_mfma_f32_16x16x32_bf16 v[28:31], v[148:151], v[182:185], v[28:31]
	v_mfma_f32_16x16x32_bf16 v[24:27], v[174:177], v[182:185], v[24:27]
	v_mfma_f32_16x16x32_bf16 v[20:23], v[148:151], v[190:193], v[20:23]
	v_mfma_f32_16x16x32_bf16 v[16:19], v[174:177], v[190:193], v[16:19]
	v_mfma_f32_16x16x32_bf16 v[12:15], v[148:151], v[206:209], v[12:15]
	v_mfma_f32_16x16x32_bf16 v[8:11], v[174:177], v[206:209], v[8:11]
	v_mfma_f32_16x16x32_bf16 v[4:7], v[148:151], v[214:217], v[4:7]
	v_mfma_f32_16x16x32_bf16 v[0:3], v[174:177], v[214:217], v[0:3]
	s_setprio 0
	s_barrier
; #define PG8_STAGE(bufoff, gbase, voff) do { _Pragma("unroll") for (int _i = 0; _i < 2; ++_i) \
;         __builtin_amdgcn_global_load_lds((const unsigned*)((const char*)(gbase) + (voff)[_i]), (PG8_LAS unsigned*)(lds + (bufoff) + ldsw + _i * 8192), 16, 0, 0); } while (0)
; #define PG8_LDA(dst, b, h) do { _Pragma("unroll") for (int m = 0; m < 4; ++m) _Pragma("unroll") for (int k = 0; k < 2; ++k) dst[m][k] = *(const PG8_LAS bf16x8*)(lds + PG8_SA(b, h) + aoff + m * 2048 + k * 1024); } while (0)
; #define PG8_LDB(dst, b, h) do { _Pragma("unroll") for (int n = 0; n < 2; ++n) _Pragma("unroll") for (int k = 0; k < 2; ++k) dst[n][k] = *(const PG8_LAS bf16x8*)(lds + PG8_SB(b, h) + boff + n * 2048 + k * 1024); } while (0)
; template <class Epi, class Sched, bool ALIGN_EPI = false, bool SP2 = false>
; __device__ __forceinline__ void gemm_phase(PG8_LAS unsigned char* lds, const Gemm g, const Sched& S, const Epi& E) {
;     ...
;         for (int t = 0; t < nt; t += 2) {
;             const bool last = (t == nt - 2);
;             const char* a1 = cA + (size_t)(t + 1) * kstep;
;             const char* a2 = last ? nA : cA + (size_t)(t + 2) * kstep; const char* b2 = last ? nB : cB + (size_t)(t + 2) * kstep;
;             const char* a3 = a2 + kstep; const char* b3 = b2 + kstep;
;             if (last && has_next) S.a_ready(nxt);
;             if constexpr (SP2) {
;             PG8_LDB(B0, 0, 0); PG8_LDB(B1, 0, 1); PG8_SCHED; PG8_LDA(At, 0, 0); PG8_STAGE(PG8_SA(1, 1), a1 + hstep, voffA);
;             PG8_WAIT_V(8); PG8_WAIT_L(0); PG8_BAR; PG8_MMA(0, 0, At, B0); PG8_MMA(0, 1, At, B1); PG8_BAR; PG8_SCHED;
;             PG8_LDA(At, 0, 1); PG8_STAGE(PG8_SB(0, 0), b2, voffB); PG8_STAGE(PG8_SB(0, 1), b2 + hstep, voffB); PG8_STAGE(PG8_SA(0, 0), a2, voffA);
;             PG8_WAIT_V(8); PG8_WAIT_L(0); PG8_BAR; PG8_MMA(1, 0, At, B0); PG8_MMA(1, 1, At, B1); PG8_BAR; PG8_SCHED;
;             PG8_LDB(B0, 1, 0); PG8_LDB(B1, 1, 1); PG8_SCHED; PG8_LDA(At, 1, 0); PG8_STAGE(PG8_SA(0, 1), a2 + hstep, voffA);
;             PG8_WAIT_V(8); PG8_WAIT_L(0); PG8_BAR; PG8_MMA(0, 0, At, B0); PG8_MMA(0, 1, At, B1); PG8_BAR; PG8_SCHED;
;             PG8_LDA(At, 1, 1); PG8_STAGE(PG8_SB(1, 0), b3, voffB); PG8_STAGE(PG8_SB(1, 1), b3 + hstep, voffB); PG8_STAGE(PG8_SA(1, 0), a3, voffA);
;             PG8_WAIT_V(8); PG8_WAIT_L(0); PG8_BAR; PG8_MMA(1, 0, At, B0); PG8_MMA(1, 1, At, B1); PG8_BAR; PG8_SCHED;
	s_add_i32 s33, 0, 0x18000
	s_add_i32 s34, 0, 0x1c000
	v_add_u32_e32 v140, s33, v201
	v_add_u32_e32 v153, s34, v201
	ds_read_b128 v[128:131], v140
	ds_read_b128 v[132:135], v140 offset:1024
	ds_read_b128 v[136:139], v140 offset:2048
	ds_read_b128 v[140:143], v140 offset:3072
	ds_read_b128 v[144:147], v153
	ds_read_b128 v[148:151], v153 offset:1024
	ds_read_b128 v[170:173], v153 offset:2048
	ds_read_b128 v[174:177], v153 offset:3072
	s_add_u32 s46, s46, 0xb0000
	s_addc_u32 s47, s47, 0
	s_mov_b32 m0, s60
	ds_read_b128 v[178:181], v205 offset:32768
	ds_read_b128 v[182:185], v205 offset:33792
	ds_read_b128 v[186:189], v205 offset:34816
	ds_read_b128 v[190:193], v205 offset:35840
	ds_read_b128 v[194:197], v205 offset:36864
	ds_read_b128 v[206:209], v205 offset:37888
	ds_read_b128 v[210:213], v205 offset:38912
	ds_read_b128 v[214:217], v205 offset:39936
	global_load_lds_dwordx4 v154, s[46:47]
	s_mov_b32 m0, s61
	s_nop 0
	global_load_lds_dwordx4 v158, s[46:47]
	s_waitcnt vmcnt(8)
	s_waitcnt lgkmcnt(0)
	s_barrier
	s_setprio 1
	s_waitcnt lgkmcnt(0)
	v_mfma_f32_16x16x32_bf16 v[124:127], v[128:131], v[178:181], v[124:127]
	v_mfma_f32_16x16x32_bf16 v[120:123], v[136:139], v[178:181], v[120:123]
	v_mfma_f32_16x16x32_bf16 v[116:119], v[128:131], v[186:189], v[116:119]
	v_mfma_f32_16x16x32_bf16 v[112:115], v[136:139], v[186:189], v[112:115]
	v_mfma_f32_16x16x32_bf16 v[108:111], v[128:131], v[194:197], v[108:111]
	v_mfma_f32_16x16x32_bf16 v[104:107], v[136:139], v[194:197], v[104:107]
	v_mfma_f32_16x16x32_bf16 v[100:103], v[128:131], v[210:213], v[100:103]
	v_mfma_f32_16x16x32_bf16 v[96:99], v[136:139], v[210:213], v[96:99]
	v_mfma_f32_16x16x32_bf16 v[124:127], v[132:135], v[182:185], v[124:127]
	v_mfma_f32_16x16x32_bf16 v[120:123], v[140:143], v[182:185], v[120:123]
	v_mfma_f32_16x16x32_bf16 v[116:119], v[132:135], v[190:193], v[116:119]
	v_mfma_f32_16x16x32_bf16 v[112:115], v[140:143], v[190:193], v[112:115]
	v_mfma_f32_16x16x32_bf16 v[108:111], v[132:135], v[206:209], v[108:111]
	v_mfma_f32_16x16x32_bf16 v[104:107], v[140:143], v[206:209], v[104:107]
	v_mfma_f32_16x16x32_bf16 v[100:103], v[132:135], v[214:217], v[100:103]
	v_mfma_f32_16x16x32_bf16 v[96:99], v[140:143], v[214:217], v[96:99]
	s_setprio 0
	s_setprio 1
	v_mfma_f32_16x16x32_bf16 v[68:71], v[144:147], v[178:181], v[68:71]
	v_mfma_f32_16x16x32_bf16 v[64:67], v[170:173], v[178:181], v[64:67]
	v_mfma_f32_16x16x32_bf16 v[60:63], v[144:147], v[186:189], v[60:63]
	v_mfma_f32_16x16x32_bf16 v[52:55], v[170:173], v[186:189], v[52:55]
	v_mfma_f32_16x16x32_bf16 v[44:47], v[144:147], v[194:197], v[44:47]
	v_mfma_f32_16x16x32_bf16 v[40:43], v[170:173], v[194:197], v[40:43]
	v_mfma_f32_16x16x32_bf16 v[36:39], v[144:147], v[210:213], v[36:39]
	v_mfma_f32_16x16x32_bf16 v[32:35], v[170:173], v[210:213], v[32:35]
	v_mfma_f32_16x16x32_bf16 v[68:71], v[148:151], v[182:185], v[68:71]
	v_mfma_f32_16x16x32_bf16 v[64:67], v[174:177], v[182:185], v[64:67]
	v_mfma_f32_16x16x32_bf16 v[60:63], v[148:151], v[190:193], v[60:63]
	v_mfma_f32_16x16x32_bf16 v[52:55], v[174:177], v[190:193], v[52:55]
	v_mfma_f32_16x16x32_bf16 v[44:47], v[148:151], v[206:209], v[44:47]
	v_mfma_f32_16x16x32_bf16 v[40:43], v[174:177], v[206:209], v[40:43]
	v_mfma_f32_16x16x32_bf16 v[36:39], v[148:151], v[214:217], v[36:39]
	v_mfma_f32_16x16x32_bf16 v[32:35], v[174:177], v[214:217], v[32:35]
	s_setprio 0
	s_barrier
	s_add_i32 s33, s33, s56
	s_mov_b32 m0, s33
	ds_read_b128 v[178:181], v205 offset:49152
	ds_read_b128 v[182:185], v205 offset:50176
	ds_read_b128 v[186:189], v205 offset:51200
	ds_read_b128 v[190:193], v205 offset:52224
	ds_read_b128 v[194:197], v205 offset:53248
	ds_read_b128 v[206:209], v205 offset:54272
	ds_read_b128 v[210:213], v205 offset:55296
	ds_read_b128 v[214:217], v205 offset:56320
	global_load_lds_dwordx4 v156, s[64:65]
	s_add_i32 m0, s33, 0x2000
	s_add_u32 s44, s44, 0xb0080
	s_addc_u32 s45, s45, 0
	s_add_i32 s33, s34, s56
	global_load_lds_dwordx4 v160, s[64:65]
	s_mov_b32 m0, s33
	s_nop 0
	global_load_lds_dwordx4 v156, s[44:45]
	s_add_i32 m0, s33, 0x2000
	s_nop 0
	global_load_lds_dwordx4 v160, s[44:45]
	s_mov_b32 m0, s72
	s_nop 0
	global_load_lds_dwordx4 v154, s[84:85]
	s_mov_b32 m0, s73
	s_nop 0
	global_load_lds_dwordx4 v158, s[84:85]
	s_waitcnt vmcnt(8)
	s_waitcnt lgkmcnt(0)
	s_barrier
	s_setprio 1
	s_waitcnt lgkmcnt(0)
	v_mfma_f32_16x16x32_bf16 v[92:95], v[128:131], v[178:181], v[92:95]
	v_mfma_f32_16x16x32_bf16 v[88:91], v[136:139], v[178:181], v[88:91]
	v_mfma_f32_16x16x32_bf16 v[84:87], v[128:131], v[186:189], v[84:87]
	v_mfma_f32_16x16x32_bf16 v[80:83], v[136:139], v[186:189], v[80:83]
	v_mfma_f32_16x16x32_bf16 v[76:79], v[128:131], v[194:197], v[76:79]
	v_mfma_f32_16x16x32_bf16 v[72:75], v[136:139], v[194:197], v[72:75]
	v_mfma_f32_16x16x32_bf16 v[56:59], v[128:131], v[210:213], v[56:59]
	v_mfma_f32_16x16x32_bf16 v[48:51], v[136:139], v[210:213], v[48:51]
	v_mfma_f32_16x16x32_bf16 v[92:95], v[132:135], v[182:185], v[92:95]
	v_mfma_f32_16x16x32_bf16 v[88:91], v[140:143], v[182:185], v[88:91]
	v_mfma_f32_16x16x32_bf16 v[84:87], v[132:135], v[190:193], v[84:87]
	v_mfma_f32_16x16x32_bf16 v[80:83], v[140:143], v[190:193], v[80:83]
	v_mfma_f32_16x16x32_bf16 v[76:79], v[132:135], v[206:209], v[76:79]
	v_mfma_f32_16x16x32_bf16 v[72:75], v[140:143], v[206:209], v[72:75]
	v_mfma_f32_16x16x32_bf16 v[56:59], v[132:135], v[214:217], v[56:59]
	v_mfma_f32_16x16x32_bf16 v[48:51], v[140:143], v[214:217], v[48:51]
	s_setprio 0
	s_setprio 1
	v_mfma_f32_16x16x32_bf16 v[28:31], v[144:147], v[178:181], v[28:31]
	v_mfma_f32_16x16x32_bf16 v[24:27], v[170:173], v[178:181], v[24:27]
	v_mfma_f32_16x16x32_bf16 v[20:23], v[144:147], v[186:189], v[20:23]
	v_mfma_f32_16x16x32_bf16 v[16:19], v[170:173], v[186:189], v[16:19]
	v_mfma_f32_16x16x32_bf16 v[12:15], v[144:147], v[194:197], v[12:15]
	v_mfma_f32_16x16x32_bf16 v[8:11], v[170:173], v[194:197], v[8:11]
	v_mfma_f32_16x16x32_bf16 v[4:7], v[144:147], v[210:213], v[4:7]
	v_mfma_f32_16x16x32_bf16 v[0:3], v[170:173], v[210:213], v[0:3]
	v_mfma_f32_16x16x32_bf16 v[28:31], v[148:151], v[182:185], v[28:31]
	v_mfma_f32_16x16x32_bf16 v[24:27], v[174:177], v[182:185], v[24:27]
	v_mfma_f32_16x16x32_bf16 v[20:23], v[148:151], v[190:193], v[20:23]
	v_mfma_f32_16x16x32_bf16 v[16:19], v[174:177], v[190:193], v[16:19]
	v_mfma_f32_16x16x32_bf16 v[12:15], v[148:151], v[206:209], v[12:15]
	v_mfma_f32_16x16x32_bf16 v[8:11], v[174:177], v[206:209], v[8:11]
	v_mfma_f32_16x16x32_bf16 v[4:7], v[148:151], v[214:217], v[4:7]
	v_mfma_f32_16x16x32_bf16 v[0:3], v[174:177], v[214:217], v[0:3]
	s_setprio 0
	s_barrier
	s_add_i32 s90, s90, 2
	s_add_u32 s42, s42, 0x100
	s_addc_u32 s43, s43, 0
	s_add_u32 s86, s86, 0x100
	s_addc_u32 s87, s87, 0
	s_cmp_gt_u32 s90, 41
	s_cbranch_scc0 .LBB0_789
	s_and_b64 vcc, exec, s[20:21]
	s_cbranch_vccz .LBB0_792
	s_barrier

; #define PG8_STAGE(bufoff, gbase, voff) do { _Pragma("unroll") for (int _i = 0; _i < 2; ++_i) \
;         __builtin_amdgcn_global_load_lds((const unsigned*)((const char*)(gbase) + (voff)[_i]), (PG8_LAS unsigned*)(lds + (bufoff) + ldsw + _i * 8192), 16, 0, 0); } while (0)
; #define PG8_LDA(dst, b, h) do { _Pragma("unroll") for (int m = 0; m < 4; ++m) _Pragma("unroll") for (int k = 0; k < 2; ++k) dst[m][k] = *(const PG8_LAS bf16x8*)(lds + PG8_SA(b, h) + aoff + m * 2048 + k * 1024); } while (0)
; #define PG8_LDB(dst, b, h) do { _Pragma("unroll") for (int n = 0; n < 2; ++n) _Pragma("unroll") for (int k = 0; k < 2; ++k) dst[n][k] = *(const PG8_LAS bf16x8*)(lds + PG8_SB(b, h) + boff + n * 2048 + k * 1024); } while (0)
; #define PG8_MMA(ai, bj, At, Bt) do { __builtin_amdgcn_s_setprio(1); _Pragma("unroll") for (int m = 0; m < 4; ++m) _Pragma("unroll") for (int n = 0; n < 2; ++n) _Pragma("unroll") for (int k = 0; k < 2; ++k) \
;         acc[ai][bj][m][n] = __builtin_amdgcn_mfma_f32_16x16x32_bf16(Bt[n][k], At[m][k], acc[ai][bj][m][n], 0, 0, 0); __builtin_amdgcn_s_setprio(0); } while (0)
; #define PG8_WAIT_V(n) asm volatile("s_waitcnt vmcnt(" #n ")" ::: "memory")
; #define PG8_WAIT_L(n) asm volatile("s_waitcnt lgkmcnt(" #n ")" ::: "memory")
; template <class Epi, class Sched, bool ALIGN_EPI = false, bool SP2 = false>
; __device__ __forceinline__ void gemm_phase(PG8_LAS unsigned char* lds, const Gemm g, const Sched& S, const Epi& E) {
;     ...
;             const bool last = (t == nt - 2);
;             const char* a1 = cA + (size_t)(t + 1) * kstep;
;             const char* a2 = last ? nA : cA + (size_t)(t + 2) * kstep; const char* b2 = last ? nB : cB + (size_t)(t + 2) * kstep;
;             const char* a3 = a2 + kstep; const char* b3 = b2 + kstep;
;             if (last && has_next) S.a_ready(nxt);
;             if constexpr (SP2) {
;             PG8_LDB(B0, 0, 0); PG8_LDB(B1, 0, 1); PG8_SCHED; PG8_LDA(At, 0, 0); PG8_STAGE(PG8_SA(1, 1), a1 + hstep, voffA);
;             PG8_WAIT_V(8); PG8_WAIT_L(0); PG8_BAR; PG8_MMA(0, 0, At, B0); PG8_MMA(0, 1, At, B1); PG8_BAR; PG8_SCHED;
;             PG8_LDA(At, 0, 1); PG8_STAGE(PG8_SB(0, 0), b2, voffB); PG8_STAGE(PG8_SB(0, 1), b2 + hstep, voffB); PG8_STAGE(PG8_SA(0, 0), a2, voffA);
;             PG8_WAIT_V(8); PG8_WAIT_L(0); PG8_BAR; PG8_MMA(1, 0, At, B0); PG8_MMA(1, 1, At, B1); PG8_BAR; PG8_SCHED;
.LBB0_915:
	ds_read_b128 v[144:147], v159
	ds_read_b128 v[148:151], v159 offset:1024
	ds_read_b128 v[162:165], v159 offset:2048
	ds_read_b128 v[166:169], v159 offset:3072
	ds_read_b128 v[170:173], v160
	ds_read_b128 v[174:177], v160 offset:1024
	ds_read_b128 v[178:181], v160 offset:2048
	ds_read_b128 v[182:185], v160 offset:3072
	s_add_u32 s33, s54, 0xfffc0080
	s_addc_u32 s34, s55, -1
	s_cmp_eq_u32 s91, 12
	s_cselect_b32 s59, s5, s34
	s_cselect_b32 s58, s45, s33
	s_cselect_b32 s57, s43, s90
	s_cselect_b32 s56, s86, s87
	s_add_i32 m0, s53, 0xc000
	ds_read_b128 v[186:189], v161
	ds_read_b128 v[190:193], v161 offset:1024
	ds_read_b128 v[194:197], v161 offset:2048
	ds_read_b128 v[198:201], v161 offset:3072
	ds_read_b128 v[202:205], v161 offset:4096
	ds_read_b128 v[206:209], v161 offset:5120
	ds_read_b128 v[210:213], v161 offset:6144
	ds_read_b128 v[214:217], v161 offset:7168
	global_load_lds_dwordx4 v136, s[54:55]
	s_add_i32 m0, s53, 0xe000
	s_nop 0
	global_load_lds_dwordx4 v138, s[54:55]
	s_waitcnt vmcnt(8)
	s_waitcnt lgkmcnt(0)
	s_barrier
	s_setprio 1
	s_waitcnt lgkmcnt(0)
	v_mfma_f32_16x16x32_bf16 v[124:127], v[144:147], v[186:189], v[124:127]
	v_mfma_f32_16x16x32_bf16 v[120:123], v[162:165], v[186:189], v[120:123]
	v_mfma_f32_16x16x32_bf16 v[108:111], v[144:147], v[194:197], v[108:111]
	v_mfma_f32_16x16x32_bf16 v[104:107], v[162:165], v[194:197], v[104:107]
	v_mfma_f32_16x16x32_bf16 v[92:95], v[144:147], v[202:205], v[92:95]
	v_mfma_f32_16x16x32_bf16 v[88:91], v[162:165], v[202:205], v[88:91]
	v_mfma_f32_16x16x32_bf16 v[76:79], v[144:147], v[210:213], v[76:79]
	v_mfma_f32_16x16x32_bf16 v[72:75], v[162:165], v[210:213], v[72:75]
	v_mfma_f32_16x16x32_bf16 v[124:127], v[148:151], v[190:193], v[124:127]
	v_mfma_f32_16x16x32_bf16 v[120:123], v[166:169], v[190:193], v[120:123]
	v_mfma_f32_16x16x32_bf16 v[108:111], v[148:151], v[198:201], v[108:111]
	v_mfma_f32_16x16x32_bf16 v[104:107], v[166:169], v[198:201], v[104:107]
	v_mfma_f32_16x16x32_bf16 v[92:95], v[148:151], v[206:209], v[92:95]
	v_mfma_f32_16x16x32_bf16 v[88:91], v[166:169], v[206:209], v[88:91]
	v_mfma_f32_16x16x32_bf16 v[76:79], v[148:151], v[214:217], v[76:79]
	v_mfma_f32_16x16x32_bf16 v[72:75], v[166:169], v[214:217], v[72:75]
	s_setprio 0
	s_setprio 1
	v_mfma_f32_16x16x32_bf16 v[116:119], v[170:173], v[186:189], v[116:119]
	v_mfma_f32_16x16x32_bf16 v[112:115], v[178:181], v[186:189], v[112:115]
	v_mfma_f32_16x16x32_bf16 v[100:103], v[170:173], v[194:197], v[100:103]
	v_mfma_f32_16x16x32_bf16 v[96:99], v[178:181], v[194:197], v[96:99]
	v_mfma_f32_16x16x32_bf16 v[84:87], v[170:173], v[202:205], v[84:87]
	v_mfma_f32_16x16x32_bf16 v[80:83], v[178:181], v[202:205], v[80:83]
	v_mfma_f32_16x16x32_bf16 v[68:71], v[170:173], v[210:213], v[68:71]
	v_mfma_f32_16x16x32_bf16 v[64:67], v[178:181], v[210:213], v[64:67]
	v_mfma_f32_16x16x32_bf16 v[116:119], v[174:177], v[190:193], v[116:119]
	v_mfma_f32_16x16x32_bf16 v[112:115], v[182:185], v[190:193], v[112:115]
	v_mfma_f32_16x16x32_bf16 v[100:103], v[174:177], v[198:201], v[100:103]
	v_mfma_f32_16x16x32_bf16 v[96:99], v[182:185], v[198:201], v[96:99]
	v_mfma_f32_16x16x32_bf16 v[84:87], v[174:177], v[206:209], v[84:87]
	v_mfma_f32_16x16x32_bf16 v[80:83], v[182:185], v[206:209], v[80:83]
	v_mfma_f32_16x16x32_bf16 v[68:71], v[174:177], v[214:217], v[68:71]
	v_mfma_f32_16x16x32_bf16 v[64:67], v[182:185], v[214:217], v[64:67]
	s_setprio 0
	s_barrier
	s_add_i32 s33, s78, s62
	s_add_u32 s80, s56, s20
	s_addc_u32 s81, s57, s21
	s_mov_b32 m0, s33
	ds_read_b128 v[186:189], v161 offset:16384
	ds_read_b128 v[190:193], v161 offset:17408
	ds_read_b128 v[194:197], v161 offset:18432
	ds_read_b128 v[198:201], v161 offset:19456
	ds_read_b128 v[202:205], v161 offset:20480
	ds_read_b128 v[206:209], v161 offset:21504
	ds_read_b128 v[210:213], v161 offset:22528
	ds_read_b128 v[214:217], v161 offset:23552
	global_load_lds_dwordx4 v130, s[56:57]
	s_add_i32 m0, s33, 0x2000
	s_add_u32 s92, s56, 0x40000
	s_addc_u32 s93, s57, 0
	s_add_i32 s33, s79, s62
	global_load_lds_dwordx4 v134, s[56:57]
	s_mov_b32 m0, s33
	s_add_u32 s82, s58, s20
	s_addc_u32 s83, s59, s21
	global_load_lds_dwordx4 v130, s[92:93]
	s_add_i32 m0, s33, 0x2000
	s_nop 0
	global_load_lds_dwordx4 v134, s[92:93]
	s_mov_b32 m0, s53
	s_nop 0
	global_load_lds_dwordx4 v128, s[58:59]
	s_mov_b32 m0, s63
	s_nop 0
	global_load_lds_dwordx4 v132, s[58:59]
	s_waitcnt vmcnt(8)
	s_waitcnt lgkmcnt(0)
	s_barrier
	s_setprio 1
	s_waitcnt lgkmcnt(0)
	v_mfma_f32_16x16x32_bf16 v[60:63], v[144:147], v[186:189], v[60:63]
	v_mfma_f32_16x16x32_bf16 v[56:59], v[162:165], v[186:189], v[56:59]
	v_mfma_f32_16x16x32_bf16 v[48:51], v[144:147], v[194:197], v[48:51]
	v_mfma_f32_16x16x32_bf16 v[40:43], v[162:165], v[194:197], v[40:43]
	v_mfma_f32_16x16x32_bf16 v[32:35], v[144:147], v[202:205], v[32:35]
	v_mfma_f32_16x16x32_bf16 v[24:27], v[162:165], v[202:205], v[24:27]
	v_mfma_f32_16x16x32_bf16 v[16:19], v[144:147], v[210:213], v[16:19]
	v_mfma_f32_16x16x32_bf16 v[8:11], v[162:165], v[210:213], v[8:11]
	v_mfma_f32_16x16x32_bf16 v[60:63], v[148:151], v[190:193], v[60:63]
	v_mfma_f32_16x16x32_bf16 v[56:59], v[166:169], v[190:193], v[56:59]
	v_mfma_f32_16x16x32_bf16 v[48:51], v[148:151], v[198:201], v[48:51]
	v_mfma_f32_16x16x32_bf16 v[40:43], v[166:169], v[198:201], v[40:43]
	v_mfma_f32_16x16x32_bf16 v[32:35], v[148:151], v[206:209], v[32:35]
	v_mfma_f32_16x16x32_bf16 v[24:27], v[166:169], v[206:209], v[24:27]
	v_mfma_f32_16x16x32_bf16 v[16:19], v[148:151], v[214:217], v[16:19]
	v_mfma_f32_16x16x32_bf16 v[8:11], v[166:169], v[214:217], v[8:11]
	s_setprio 0
	s_setprio 1
	v_mfma_f32_16x16x32_bf16 v[52:55], v[170:173], v[186:189], v[52:55]
	v_mfma_f32_16x16x32_bf16 v[44:47], v[178:181], v[186:189], v[44:47]
	v_mfma_f32_16x16x32_bf16 v[36:39], v[170:173], v[194:197], v[36:39]
	v_mfma_f32_16x16x32_bf16 v[28:31], v[178:181], v[194:197], v[28:31]
	v_mfma_f32_16x16x32_bf16 v[20:23], v[170:173], v[202:205], v[20:23]
	v_mfma_f32_16x16x32_bf16 v[12:15], v[178:181], v[202:205], v[12:15]
	v_mfma_f32_16x16x32_bf16 v[4:7], v[170:173], v[210:213], v[4:7]
	v_mfma_f32_16x16x32_bf16 v[0:3], v[178:181], v[210:213], v[0:3]
	v_mfma_f32_16x16x32_bf16 v[52:55], v[174:177], v[190:193], v[52:55]
	v_mfma_f32_16x16x32_bf16 v[44:47], v[182:185], v[190:193], v[44:47]
	v_mfma_f32_16x16x32_bf16 v[36:39], v[174:177], v[198:201], v[36:39]
	v_mfma_f32_16x16x32_bf16 v[28:31], v[182:185], v[198:201], v[28:31]
	v_mfma_f32_16x16x32_bf16 v[20:23], v[174:177], v[206:209], v[20:23]
	v_mfma_f32_16x16x32_bf16 v[12:15], v[182:185], v[206:209], v[12:15]
	v_mfma_f32_16x16x32_bf16 v[4:7], v[174:177], v[214:217], v[4:7]
	v_mfma_f32_16x16x32_bf16 v[0:3], v[182:185], v[214:217], v[0:3]
	s_setprio 0
	s_barrier
; #define PG8_STAGE(bufoff, gbase, voff) do { _Pragma("unroll") for (int _i = 0; _i < 2; ++_i) \
;         __builtin_amdgcn_global_load_lds((const unsigned*)((const char*)(gbase) + (voff)[_i]), (PG8_LAS unsigned*)(lds + (bufoff) + ldsw + _i * 8192), 16, 0, 0); } while (0)
; #define PG8_LDA(dst, b, h) do { _Pragma("unroll") for (int m = 0; m < 4; ++m) _Pragma("unroll") for (int k = 0; k < 2; ++k) dst[m][k] = *(const PG8_LAS bf16x8*)(lds + PG8_SA(b, h) + aoff + m * 2048 + k * 1024); } while (0)
; #define PG8_LDB(dst, b, h) do { _Pragma("unroll") for (int n = 0; n < 2; ++n) _Pragma("unroll") for (int k = 0; k < 2; ++k) dst[n][k] = *(const PG8_LAS bf16x8*)(lds + PG8_SB(b, h) + boff + n * 2048 + k * 1024); } while (0)
; template <class Epi, class Sched, bool ALIGN_EPI = false, bool SP2 = false>
; __device__ __forceinline__ void gemm_phase(PG8_LAS unsigned char* lds, const Gemm g, const Sched& S, const Epi& E) {
;     ...
;         for (int t = 0; t < nt; t += 2) {
;             const bool last = (t == nt - 2);
;             const char* a1 = cA + (size_t)(t + 1) * kstep;
;             const char* a2 = last ? nA : cA + (size_t)(t + 2) * kstep; const char* b2 = last ? nB : cB + (size_t)(t + 2) * kstep;
;             const char* a3 = a2 + kstep; const char* b3 = b2 + kstep;
;             if (last && has_next) S.a_ready(nxt);
;             if constexpr (SP2) {
;             PG8_LDB(B0, 0, 0); PG8_LDB(B1, 0, 1); PG8_SCHED; PG8_LDA(At, 0, 0); PG8_STAGE(PG8_SA(1, 1), a1 + hstep, voffA);
;             PG8_WAIT_V(8); PG8_WAIT_L(0); PG8_BAR; PG8_MMA(0, 0, At, B0); PG8_MMA(0, 1, At, B1); PG8_BAR; PG8_SCHED;
;             PG8_LDA(At, 0, 1); PG8_STAGE(PG8_SB(0, 0), b2, voffB); PG8_STAGE(PG8_SB(0, 1), b2 + hstep, voffB); PG8_STAGE(PG8_SA(0, 0), a2, voffA);
;             PG8_WAIT_V(8); PG8_WAIT_L(0); PG8_BAR; PG8_MMA(1, 0, At, B0); PG8_MMA(1, 1, At, B1); PG8_BAR; PG8_SCHED;
;             PG8_LDB(B0, 1, 0); PG8_LDB(B1, 1, 1); PG8_SCHED; PG8_LDA(At, 1, 0); PG8_STAGE(PG8_SA(0, 1), a2 + hstep, voffA);
;             PG8_WAIT_V(8); PG8_WAIT_L(0); PG8_BAR; PG8_MMA(0, 0, At, B0); PG8_MMA(0, 1, At, B1); PG8_BAR; PG8_SCHED;
;             PG8_LDA(At, 1, 1); PG8_STAGE(PG8_SB(1, 0), b3, voffB); PG8_STAGE(PG8_SB(1, 1), b3 + hstep, voffB); PG8_STAGE(PG8_SA(1, 0), a3, voffA);
;             PG8_WAIT_V(8); PG8_WAIT_L(0); PG8_BAR; PG8_MMA(1, 0, At, B0); PG8_MMA(1, 1, At, B1); PG8_BAR; PG8_SCHED;
	s_add_i32 s33, 0, 0x18000
	v_add_u32_e32 v153, s33, v157
	s_add_i32 s34, 0, 0x1c000
	ds_read_b128 v[144:147], v153
	ds_read_b128 v[148:151], v153 offset:1024
	ds_read_b128 v[162:165], v153 offset:2048
	ds_read_b128 v[166:169], v153 offset:3072
	v_add_u32_e32 v153, s34, v157
	ds_read_b128 v[170:173], v153
	ds_read_b128 v[174:177], v153 offset:1024
	ds_read_b128 v[178:181], v153 offset:2048
	ds_read_b128 v[182:185], v153 offset:3072
	s_add_u32 s58, s58, 0x40000
	s_addc_u32 s59, s59, 0
	s_mov_b32 m0, s70
	ds_read_b128 v[186:189], v161 offset:32768
	ds_read_b128 v[190:193], v161 offset:33792
	ds_read_b128 v[194:197], v161 offset:34816
	ds_read_b128 v[198:201], v161 offset:35840
	ds_read_b128 v[202:205], v161 offset:36864
	ds_read_b128 v[206:209], v161 offset:37888
	ds_read_b128 v[210:213], v161 offset:38912
	ds_read_b128 v[214:217], v161 offset:39936
	global_load_lds_dwordx4 v128, s[58:59]
	s_mov_b32 m0, s71
	s_nop 0
	global_load_lds_dwordx4 v132, s[58:59]
	s_waitcnt vmcnt(8)
	s_waitcnt lgkmcnt(0)
	s_barrier
	s_setprio 1
	s_waitcnt lgkmcnt(0)
	v_mfma_f32_16x16x32_bf16 v[124:127], v[144:147], v[186:189], v[124:127]
	v_mfma_f32_16x16x32_bf16 v[120:123], v[162:165], v[186:189], v[120:123]
	v_mfma_f32_16x16x32_bf16 v[108:111], v[144:147], v[194:197], v[108:111]
	v_mfma_f32_16x16x32_bf16 v[104:107], v[162:165], v[194:197], v[104:107]
	v_mfma_f32_16x16x32_bf16 v[92:95], v[144:147], v[202:205], v[92:95]
	v_mfma_f32_16x16x32_bf16 v[88:91], v[162:165], v[202:205], v[88:91]
	v_mfma_f32_16x16x32_bf16 v[76:79], v[144:147], v[210:213], v[76:79]
	v_mfma_f32_16x16x32_bf16 v[72:75], v[162:165], v[210:213], v[72:75]
	v_mfma_f32_16x16x32_bf16 v[124:127], v[148:151], v[190:193], v[124:127]
	v_mfma_f32_16x16x32_bf16 v[120:123], v[166:169], v[190:193], v[120:123]
	v_mfma_f32_16x16x32_bf16 v[108:111], v[148:151], v[198:201], v[108:111]
	v_mfma_f32_16x16x32_bf16 v[104:107], v[166:169], v[198:201], v[104:107]
	v_mfma_f32_16x16x32_bf16 v[92:95], v[148:151], v[206:209], v[92:95]
	v_mfma_f32_16x16x32_bf16 v[88:91], v[166:169], v[206:209], v[88:91]
	v_mfma_f32_16x16x32_bf16 v[76:79], v[148:151], v[214:217], v[76:79]
	v_mfma_f32_16x16x32_bf16 v[72:75], v[166:169], v[214:217], v[72:75]
	s_setprio 0
	s_setprio 1
	v_mfma_f32_16x16x32_bf16 v[116:119], v[170:173], v[186:189], v[116:119]
	v_mfma_f32_16x16x32_bf16 v[112:115], v[178:181], v[186:189], v[112:115]
	v_mfma_f32_16x16x32_bf16 v[100:103], v[170:173], v[194:197], v[100:103]
	v_mfma_f32_16x16x32_bf16 v[96:99], v[178:181], v[194:197], v[96:99]
	v_mfma_f32_16x16x32_bf16 v[84:87], v[170:173], v[202:205], v[84:87]
	v_mfma_f32_16x16x32_bf16 v[80:83], v[178:181], v[202:205], v[80:83]
	v_mfma_f32_16x16x32_bf16 v[68:71], v[170:173], v[210:213], v[68:71]
	v_mfma_f32_16x16x32_bf16 v[64:67], v[178:181], v[210:213], v[64:67]
	v_mfma_f32_16x16x32_bf16 v[116:119], v[174:177], v[190:193], v[116:119]
	v_mfma_f32_16x16x32_bf16 v[112:115], v[182:185], v[190:193], v[112:115]
	v_mfma_f32_16x16x32_bf16 v[100:103], v[174:177], v[198:201], v[100:103]
	v_mfma_f32_16x16x32_bf16 v[96:99], v[182:185], v[198:201], v[96:99]
	v_mfma_f32_16x16x32_bf16 v[84:87], v[174:177], v[206:209], v[84:87]
	v_mfma_f32_16x16x32_bf16 v[80:83], v[182:185], v[206:209], v[80:83]
	v_mfma_f32_16x16x32_bf16 v[68:71], v[174:177], v[214:217], v[68:71]
	v_mfma_f32_16x16x32_bf16 v[64:67], v[182:185], v[214:217], v[64:67]
	s_setprio 0
	s_barrier
	s_add_i32 s33, s33, s62
	s_mov_b32 m0, s33
	ds_read_b128 v[186:189], v161 offset:49152
	ds_read_b128 v[190:193], v161 offset:50176
	ds_read_b128 v[194:197], v161 offset:51200
	ds_read_b128 v[198:201], v161 offset:52224
	ds_read_b128 v[202:205], v161 offset:53248
	ds_read_b128 v[206:209], v161 offset:54272
	ds_read_b128 v[210:213], v161 offset:55296
	ds_read_b128 v[214:217], v161 offset:56320
	global_load_lds_dwordx4 v130, s[80:81]
	s_add_i32 m0, s33, 0x2000
	s_add_u32 s56, s56, 0x40080
	s_addc_u32 s57, s57, 0
	s_add_i32 s33, s34, s62
	global_load_lds_dwordx4 v134, s[80:81]
	s_mov_b32 m0, s33
	s_nop 0
	global_load_lds_dwordx4 v130, s[56:57]
	s_add_i32 m0, s33, 0x2000
	s_nop 0
	global_load_lds_dwordx4 v134, s[56:57]
	s_mov_b32 m0, s75
	s_nop 0
	global_load_lds_dwordx4 v128, s[82:83]
	s_mov_b32 m0, s76
	s_nop 0
	global_load_lds_dwordx4 v132, s[82:83]
	s_waitcnt vmcnt(8)
	s_waitcnt lgkmcnt(0)
	s_barrier
	s_setprio 1
	s_waitcnt lgkmcnt(0)
	v_mfma_f32_16x16x32_bf16 v[60:63], v[144:147], v[186:189], v[60:63]
	v_mfma_f32_16x16x32_bf16 v[56:59], v[162:165], v[186:189], v[56:59]
	v_mfma_f32_16x16x32_bf16 v[48:51], v[144:147], v[194:197], v[48:51]
	v_mfma_f32_16x16x32_bf16 v[40:43], v[162:165], v[194:197], v[40:43]
	v_mfma_f32_16x16x32_bf16 v[32:35], v[144:147], v[202:205], v[32:35]
	v_mfma_f32_16x16x32_bf16 v[24:27], v[162:165], v[202:205], v[24:27]
	v_mfma_f32_16x16x32_bf16 v[16:19], v[144:147], v[210:213], v[16:19]
	v_mfma_f32_16x16x32_bf16 v[8:11], v[162:165], v[210:213], v[8:11]
	v_mfma_f32_16x16x32_bf16 v[60:63], v[148:151], v[190:193], v[60:63]
	v_mfma_f32_16x16x32_bf16 v[56:59], v[166:169], v[190:193], v[56:59]
	v_mfma_f32_16x16x32_bf16 v[48:51], v[148:151], v[198:201], v[48:51]
	v_mfma_f32_16x16x32_bf16 v[40:43], v[166:169], v[198:201], v[40:43]
	v_mfma_f32_16x16x32_bf16 v[32:35], v[148:151], v[206:209], v[32:35]
	v_mfma_f32_16x16x32_bf16 v[24:27], v[166:169], v[206:209], v[24:27]
	v_mfma_f32_16x16x32_bf16 v[16:19], v[148:151], v[214:217], v[16:19]
	v_mfma_f32_16x16x32_bf16 v[8:11], v[166:169], v[214:217], v[8:11]
	s_setprio 0
	s_setprio 1
	v_mfma_f32_16x16x32_bf16 v[52:55], v[170:173], v[186:189], v[52:55]
	v_mfma_f32_16x16x32_bf16 v[44:47], v[178:181], v[186:189], v[44:47]
	v_mfma_f32_16x16x32_bf16 v[36:39], v[170:173], v[194:197], v[36:39]
	v_mfma_f32_16x16x32_bf16 v[28:31], v[178:181], v[194:197], v[28:31]
	v_mfma_f32_16x16x32_bf16 v[20:23], v[170:173], v[202:205], v[20:23]
	v_mfma_f32_16x16x32_bf16 v[12:15], v[178:181], v[202:205], v[12:15]
	v_mfma_f32_16x16x32_bf16 v[4:7], v[170:173], v[210:213], v[4:7]
	v_mfma_f32_16x16x32_bf16 v[0:3], v[178:181], v[210:213], v[0:3]
	v_mfma_f32_16x16x32_bf16 v[52:55], v[174:177], v[190:193], v[52:55]
	v_mfma_f32_16x16x32_bf16 v[44:47], v[182:185], v[190:193], v[44:47]
	v_mfma_f32_16x16x32_bf16 v[36:39], v[174:177], v[198:201], v[36:39]
	v_mfma_f32_16x16x32_bf16 v[28:31], v[182:185], v[198:201], v[28:31]
	v_mfma_f32_16x16x32_bf16 v[20:23], v[174:177], v[206:209], v[20:23]
	v_mfma_f32_16x16x32_bf16 v[12:15], v[182:185], v[206:209], v[12:15]
	v_mfma_f32_16x16x32_bf16 v[4:7], v[174:177], v[214:217], v[4:7]
	v_mfma_f32_16x16x32_bf16 v[0:3], v[182:185], v[214:217], v[0:3]
	s_setprio 0
	s_barrier
	s_add_i32 s91, s91, 2
	s_add_u32 s54, s54, 0x100
	s_addc_u32 s55, s55, 0
	s_add_u32 s87, s87, 0x100
	s_addc_u32 s90, s90, 0
	s_cmp_gt_u32 s91, 13
	s_cbranch_scc0 .LBB0_915
	s_and_b64 vcc, exec, s[22:23]
	s_cbranch_vccz .LBB0_918
	s_barrier

; #define PG8_STAGE(bufoff, gbase, voff) do { _Pragma("unroll") for (int _i = 0; _i < 2; ++_i) \
;         __builtin_amdgcn_global_load_lds((const unsigned*)((const char*)(gbase) + (voff)[_i]), (PG8_LAS unsigned*)(lds + (bufoff) + ldsw + _i * 8192), 16, 0, 0); } while (0)
; #define PG8_LDA(dst, b, h) do { _Pragma("unroll") for (int m = 0; m < 4; ++m) _Pragma("unroll") for (int k = 0; k < 2; ++k) dst[m][k] = *(const PG8_LAS bf16x8*)(lds + PG8_SA(b, h) + aoff + m * 2048 + k * 1024); } while (0)
; #define PG8_LDB(dst, b, h) do { _Pragma("unroll") for (int n = 0; n < 2; ++n) _Pragma("unroll") for (int k = 0; k < 2; ++k) dst[n][k] = *(const PG8_LAS bf16x8*)(lds + PG8_SB(b, h) + boff + n * 2048 + k * 1024); } while (0)
; #define PG8_MMA(ai, bj, At, Bt) do { __builtin_amdgcn_s_setprio(1); _Pragma("unroll") for (int m = 0; m < 4; ++m) _Pragma("unroll") for (int n = 0; n < 2; ++n) _Pragma("unroll") for (int k = 0; k < 2; ++k) \
;         acc[ai][bj][m][n] = __builtin_amdgcn_mfma_f32_16x16x32_bf16(Bt[n][k], At[m][k], acc[ai][bj][m][n], 0, 0, 0); __builtin_amdgcn_s_setprio(0); } while (0)
; #define PG8_WAIT_V(n) asm volatile("s_waitcnt vmcnt(" #n ")" ::: "memory")
; #define PG8_WAIT_L(n) asm volatile("s_waitcnt lgkmcnt(" #n ")" ::: "memory")
; template <class Epi, class Sched, bool ALIGN_EPI = false, bool SP2 = false>
; __device__ __forceinline__ void gemm_phase(PG8_LAS unsigned char* lds, const Gemm g, const Sched& S, const Epi& E) {
;     ...
;             const bool last = (t == nt - 2);
;             const char* a1 = cA + (size_t)(t + 1) * kstep;
;             const char* a2 = last ? nA : cA + (size_t)(t + 2) * kstep; const char* b2 = last ? nB : cB + (size_t)(t + 2) * kstep;
;             const char* a3 = a2 + kstep; const char* b3 = b2 + kstep;
;             if (last && has_next) S.a_ready(nxt);
;             if constexpr (SP2) {
;             PG8_LDB(B0, 0, 0); PG8_LDB(B1, 0, 1); PG8_SCHED; PG8_LDA(At, 0, 0); PG8_STAGE(PG8_SA(1, 1), a1 + hstep, voffA);
;             PG8_WAIT_V(8); PG8_WAIT_L(0); PG8_BAR; PG8_MMA(0, 0, At, B0); PG8_MMA(0, 1, At, B1); PG8_BAR; PG8_SCHED;
;             PG8_LDA(At, 0, 1); PG8_STAGE(PG8_SB(0, 0), b2, voffB); PG8_STAGE(PG8_SB(0, 1), b2 + hstep, voffB); PG8_STAGE(PG8_SA(0, 0), a2, voffA);
;             PG8_WAIT_V(8); PG8_WAIT_L(0); PG8_BAR; PG8_MMA(1, 0, At, B0); PG8_MMA(1, 1, At, B1); PG8_BAR; PG8_SCHED;
.LBB0_1210:
	ds_read_b128 v[128:131], v181
	ds_read_b128 v[132:135], v181 offset:1024
	ds_read_b128 v[136:139], v181 offset:2048
	ds_read_b128 v[140:143], v181 offset:3072
	ds_read_b128 v[144:147], v182
	ds_read_b128 v[166:169], v182 offset:1024
	ds_read_b128 v[170:173], v182 offset:2048
	ds_read_b128 v[174:177], v182 offset:3072
	s_add_u32 s33, s4, 0xfffc0080
	s_addc_u32 s34, s5, -1
	s_cmp_eq_u32 s80, 12
	s_cselect_b32 s55, s43, s34
	s_cselect_b32 s54, s76, s33
	s_cselect_b32 s53, s41, s79
	s_cselect_b32 s52, s77, s78
	s_add_i32 m0, s49, 0xc000
	ds_read_b128 v[184:187], v183
	ds_read_b128 v[188:191], v183 offset:1024
	ds_read_b128 v[192:195], v183 offset:2048
	ds_read_b128 v[196:199], v183 offset:3072
	ds_read_b128 v[200:203], v183 offset:4096
	ds_read_b128 v[204:207], v183 offset:5120
	ds_read_b128 v[208:211], v183 offset:6144
	ds_read_b128 v[212:215], v183 offset:7168
	global_load_lds_dwordx4 v158, s[4:5]
	s_add_i32 m0, s49, 0xe000
	s_nop 0
	global_load_lds_dwordx4 v160, s[4:5]
	s_waitcnt vmcnt(8)
	s_waitcnt lgkmcnt(0)
	s_barrier
	s_setprio 1
	s_waitcnt lgkmcnt(0)
	v_mfma_f32_16x16x32_bf16 v[124:127], v[128:131], v[184:187], v[124:127]
	v_mfma_f32_16x16x32_bf16 v[120:123], v[136:139], v[184:187], v[120:123]
	v_mfma_f32_16x16x32_bf16 v[116:119], v[128:131], v[192:195], v[116:119]
	v_mfma_f32_16x16x32_bf16 v[112:115], v[136:139], v[192:195], v[112:115]
	v_mfma_f32_16x16x32_bf16 v[108:111], v[128:131], v[200:203], v[108:111]
	v_mfma_f32_16x16x32_bf16 v[104:107], v[136:139], v[200:203], v[104:107]
	v_mfma_f32_16x16x32_bf16 v[100:103], v[128:131], v[208:211], v[100:103]
	v_mfma_f32_16x16x32_bf16 v[96:99], v[136:139], v[208:211], v[96:99]
	v_mfma_f32_16x16x32_bf16 v[124:127], v[132:135], v[188:191], v[124:127]
	v_mfma_f32_16x16x32_bf16 v[120:123], v[140:143], v[188:191], v[120:123]
	v_mfma_f32_16x16x32_bf16 v[116:119], v[132:135], v[196:199], v[116:119]
	v_mfma_f32_16x16x32_bf16 v[112:115], v[140:143], v[196:199], v[112:115]
	v_mfma_f32_16x16x32_bf16 v[108:111], v[132:135], v[204:207], v[108:111]
	v_mfma_f32_16x16x32_bf16 v[104:107], v[140:143], v[204:207], v[104:107]
	v_mfma_f32_16x16x32_bf16 v[100:103], v[132:135], v[212:215], v[100:103]
	v_mfma_f32_16x16x32_bf16 v[96:99], v[140:143], v[212:215], v[96:99]
	s_setprio 0
	s_setprio 1
	v_mfma_f32_16x16x32_bf16 v[60:63], v[144:147], v[184:187], v[60:63]
	v_mfma_f32_16x16x32_bf16 v[56:59], v[170:173], v[184:187], v[56:59]
	v_mfma_f32_16x16x32_bf16 v[52:55], v[144:147], v[192:195], v[52:55]
	v_mfma_f32_16x16x32_bf16 v[48:51], v[170:173], v[192:195], v[48:51]
	v_mfma_f32_16x16x32_bf16 v[44:47], v[144:147], v[200:203], v[44:47]
	v_mfma_f32_16x16x32_bf16 v[40:43], v[170:173], v[200:203], v[40:43]
	v_mfma_f32_16x16x32_bf16 v[36:39], v[144:147], v[208:211], v[36:39]
	v_mfma_f32_16x16x32_bf16 v[32:35], v[170:173], v[208:211], v[32:35]
	v_mfma_f32_16x16x32_bf16 v[60:63], v[166:169], v[188:191], v[60:63]
	v_mfma_f32_16x16x32_bf16 v[56:59], v[174:177], v[188:191], v[56:59]
	v_mfma_f32_16x16x32_bf16 v[52:55], v[166:169], v[196:199], v[52:55]
	v_mfma_f32_16x16x32_bf16 v[48:51], v[174:177], v[196:199], v[48:51]
	v_mfma_f32_16x16x32_bf16 v[44:47], v[166:169], v[204:207], v[44:47]
	v_mfma_f32_16x16x32_bf16 v[40:43], v[174:177], v[204:207], v[40:43]
	v_mfma_f32_16x16x32_bf16 v[36:39], v[166:169], v[212:215], v[36:39]
	v_mfma_f32_16x16x32_bf16 v[32:35], v[174:177], v[212:215], v[32:35]
	s_setprio 0
	s_barrier
	s_add_i32 s33, s69, s58
	s_add_u32 s86, s52, s20
	s_addc_u32 s87, s53, s21
	s_mov_b32 m0, s33
	ds_read_b128 v[184:187], v183 offset:16384
	ds_read_b128 v[188:191], v183 offset:17408
	ds_read_b128 v[192:195], v183 offset:18432
	ds_read_b128 v[196:199], v183 offset:19456
	ds_read_b128 v[200:203], v183 offset:20480
	ds_read_b128 v[204:207], v183 offset:21504
	ds_read_b128 v[208:211], v183 offset:22528
	ds_read_b128 v[212:215], v183 offset:23552
	global_load_lds_dwordx4 v150, s[52:53]
	s_add_i32 m0, s33, 0x2000
	s_add_u32 s82, s52, 0x40000
	s_addc_u32 s83, s53, 0
	s_add_i32 s33, s70, s58
	global_load_lds_dwordx4 v156, s[52:53]
	s_mov_b32 m0, s33
	s_add_u32 s88, s54, s20
	s_addc_u32 s89, s55, s21
	global_load_lds_dwordx4 v150, s[82:83]
	s_add_i32 m0, s33, 0x2000
	s_nop 0
	global_load_lds_dwordx4 v156, s[82:83]
	s_mov_b32 m0, s49
	s_nop 0
	global_load_lds_dwordx4 v148, s[54:55]
	s_mov_b32 m0, s60
	s_nop 0
	global_load_lds_dwordx4 v154, s[54:55]
	s_waitcnt vmcnt(8)
	s_waitcnt lgkmcnt(0)
	s_barrier
	s_setprio 1
	s_waitcnt lgkmcnt(0)
	v_mfma_f32_16x16x32_bf16 v[92:95], v[128:131], v[184:187], v[92:95]
	v_mfma_f32_16x16x32_bf16 v[88:91], v[136:139], v[184:187], v[88:91]
	v_mfma_f32_16x16x32_bf16 v[84:87], v[128:131], v[192:195], v[84:87]
	v_mfma_f32_16x16x32_bf16 v[80:83], v[136:139], v[192:195], v[80:83]
	v_mfma_f32_16x16x32_bf16 v[76:79], v[128:131], v[200:203], v[76:79]
	v_mfma_f32_16x16x32_bf16 v[72:75], v[136:139], v[200:203], v[72:75]
	v_mfma_f32_16x16x32_bf16 v[68:71], v[128:131], v[208:211], v[68:71]
	v_mfma_f32_16x16x32_bf16 v[64:67], v[136:139], v[208:211], v[64:67]
	v_mfma_f32_16x16x32_bf16 v[92:95], v[132:135], v[188:191], v[92:95]
	v_mfma_f32_16x16x32_bf16 v[88:91], v[140:143], v[188:191], v[88:91]
	v_mfma_f32_16x16x32_bf16 v[84:87], v[132:135], v[196:199], v[84:87]
	v_mfma_f32_16x16x32_bf16 v[80:83], v[140:143], v[196:199], v[80:83]
	v_mfma_f32_16x16x32_bf16 v[76:79], v[132:135], v[204:207], v[76:79]
	v_mfma_f32_16x16x32_bf16 v[72:75], v[140:143], v[204:207], v[72:75]
	v_mfma_f32_16x16x32_bf16 v[68:71], v[132:135], v[212:215], v[68:71]
	v_mfma_f32_16x16x32_bf16 v[64:67], v[140:143], v[212:215], v[64:67]
	s_setprio 0
	s_setprio 1
	v_mfma_f32_16x16x32_bf16 v[28:31], v[144:147], v[184:187], v[28:31]
	v_mfma_f32_16x16x32_bf16 v[24:27], v[170:173], v[184:187], v[24:27]
	v_mfma_f32_16x16x32_bf16 v[20:23], v[144:147], v[192:195], v[20:23]
	v_mfma_f32_16x16x32_bf16 v[16:19], v[170:173], v[192:195], v[16:19]
	v_mfma_f32_16x16x32_bf16 v[12:15], v[144:147], v[200:203], v[12:15]
	v_mfma_f32_16x16x32_bf16 v[8:11], v[170:173], v[200:203], v[8:11]
	v_mfma_f32_16x16x32_bf16 v[4:7], v[144:147], v[208:211], v[4:7]
	v_mfma_f32_16x16x32_bf16 v[0:3], v[170:173], v[208:211], v[0:3]
	v_mfma_f32_16x16x32_bf16 v[28:31], v[166:169], v[188:191], v[28:31]
	v_mfma_f32_16x16x32_bf16 v[24:27], v[174:177], v[188:191], v[24:27]
	v_mfma_f32_16x16x32_bf16 v[20:23], v[166:169], v[196:199], v[20:23]
	v_mfma_f32_16x16x32_bf16 v[16:19], v[174:177], v[196:199], v[16:19]
	v_mfma_f32_16x16x32_bf16 v[12:15], v[166:169], v[204:207], v[12:15]
	v_mfma_f32_16x16x32_bf16 v[8:11], v[174:177], v[204:207], v[8:11]
	v_mfma_f32_16x16x32_bf16 v[4:7], v[166:169], v[212:215], v[4:7]
	v_mfma_f32_16x16x32_bf16 v[0:3], v[174:177], v[212:215], v[0:3]
	s_setprio 0
	s_barrier
; #define PG8_STAGE(bufoff, gbase, voff) do { _Pragma("unroll") for (int _i = 0; _i < 2; ++_i) \
;         __builtin_amdgcn_global_load_lds((const unsigned*)((const char*)(gbase) + (voff)[_i]), (PG8_LAS unsigned*)(lds + (bufoff) + ldsw + _i * 8192), 16, 0, 0); } while (0)
; #define PG8_LDA(dst, b, h) do { _Pragma("unroll") for (int m = 0; m < 4; ++m) _Pragma("unroll") for (int k = 0; k < 2; ++k) dst[m][k] = *(const PG8_LAS bf16x8*)(lds + PG8_SA(b, h) + aoff + m * 2048 + k * 1024); } while (0)
; #define PG8_LDB(dst, b, h) do { _Pragma("unroll") for (int n = 0; n < 2; ++n) _Pragma("unroll") for (int k = 0; k < 2; ++k) dst[n][k] = *(const PG8_LAS bf16x8*)(lds + PG8_SB(b, h) + boff + n * 2048 + k * 1024); } while (0)
; template <class Epi, class Sched, bool ALIGN_EPI = false, bool SP2 = false>
; __device__ __forceinline__ void gemm_phase(PG8_LAS unsigned char* lds, const Gemm g, const Sched& S, const Epi& E) {
;     ...
;         for (int t = 0; t < nt; t += 2) {
;             const bool last = (t == nt - 2);
;             const char* a1 = cA + (size_t)(t + 1) * kstep;
;             const char* a2 = last ? nA : cA + (size_t)(t + 2) * kstep; const char* b2 = last ? nB : cB + (size_t)(t + 2) * kstep;
;             const char* a3 = a2 + kstep; const char* b3 = b2 + kstep;
;             if (last && has_next) S.a_ready(nxt);
;             if constexpr (SP2) {
;             PG8_LDB(B0, 0, 0); PG8_LDB(B1, 0, 1); PG8_SCHED; PG8_LDA(At, 0, 0); PG8_STAGE(PG8_SA(1, 1), a1 + hstep, voffA);
;             PG8_WAIT_V(8); PG8_WAIT_L(0); PG8_BAR; PG8_MMA(0, 0, At, B0); PG8_MMA(0, 1, At, B1); PG8_BAR; PG8_SCHED;
;             PG8_LDA(At, 0, 1); PG8_STAGE(PG8_SB(0, 0), b2, voffB); PG8_STAGE(PG8_SB(0, 1), b2 + hstep, voffB); PG8_STAGE(PG8_SA(0, 0), a2, voffA);
;             PG8_WAIT_V(8); PG8_WAIT_L(0); PG8_BAR; PG8_MMA(1, 0, At, B0); PG8_MMA(1, 1, At, B1); PG8_BAR; PG8_SCHED;
;             PG8_LDB(B0, 1, 0); PG8_LDB(B1, 1, 1); PG8_SCHED; PG8_LDA(At, 1, 0); PG8_STAGE(PG8_SA(0, 1), a2 + hstep, voffA);
;             PG8_WAIT_V(8); PG8_WAIT_L(0); PG8_BAR; PG8_MMA(0, 0, At, B0); PG8_MMA(0, 1, At, B1); PG8_BAR; PG8_SCHED;
;             PG8_LDA(At, 1, 1); PG8_STAGE(PG8_SB(1, 0), b3, voffB); PG8_STAGE(PG8_SB(1, 1), b3 + hstep, voffB); PG8_STAGE(PG8_SA(1, 0), a3, voffA);
;             PG8_WAIT_V(8); PG8_WAIT_L(0); PG8_BAR; PG8_MMA(1, 0, At, B0); PG8_MMA(1, 1, At, B1); PG8_BAR; PG8_SCHED;
	s_add_i32 s33, 0, 0x18000
	s_add_i32 s34, 0, 0x1c000
	v_add_u32_e32 v140, s33, v179
	v_add_u32_e32 v153, s34, v179
	ds_read_b128 v[128:131], v140
	ds_read_b128 v[132:135], v140 offset:1024
	ds_read_b128 v[136:139], v140 offset:2048
	ds_read_b128 v[140:143], v140 offset:3072
	ds_read_b128 v[144:147], v153
	ds_read_b128 v[166:169], v153 offset:1024
	ds_read_b128 v[170:173], v153 offset:2048
	ds_read_b128 v[174:177], v153 offset:3072
	s_add_u32 s54, s54, 0x40000
	s_addc_u32 s55, s55, 0
	s_mov_b32 m0, s61
	ds_read_b128 v[184:187], v183 offset:32768
	ds_read_b128 v[188:191], v183 offset:33792
	ds_read_b128 v[192:195], v183 offset:34816
	ds_read_b128 v[196:199], v183 offset:35840
	ds_read_b128 v[200:203], v183 offset:36864
	ds_read_b128 v[204:207], v183 offset:37888
	ds_read_b128 v[208:211], v183 offset:38912
	ds_read_b128 v[212:215], v183 offset:39936
	global_load_lds_dwordx4 v148, s[54:55]
	s_mov_b32 m0, s62
	s_nop 0
	global_load_lds_dwordx4 v154, s[54:55]
	s_waitcnt vmcnt(8)
	s_waitcnt lgkmcnt(0)
	s_barrier
	s_setprio 1
	s_waitcnt lgkmcnt(0)
	v_mfma_f32_16x16x32_bf16 v[124:127], v[128:131], v[184:187], v[124:127]
	v_mfma_f32_16x16x32_bf16 v[120:123], v[136:139], v[184:187], v[120:123]
	v_mfma_f32_16x16x32_bf16 v[116:119], v[128:131], v[192:195], v[116:119]
	v_mfma_f32_16x16x32_bf16 v[112:115], v[136:139], v[192:195], v[112:115]
	v_mfma_f32_16x16x32_bf16 v[108:111], v[128:131], v[200:203], v[108:111]
	v_mfma_f32_16x16x32_bf16 v[104:107], v[136:139], v[200:203], v[104:107]
	v_mfma_f32_16x16x32_bf16 v[100:103], v[128:131], v[208:211], v[100:103]
	v_mfma_f32_16x16x32_bf16 v[96:99], v[136:139], v[208:211], v[96:99]
	v_mfma_f32_16x16x32_bf16 v[124:127], v[132:135], v[188:191], v[124:127]
	v_mfma_f32_16x16x32_bf16 v[120:123], v[140:143], v[188:191], v[120:123]
	v_mfma_f32_16x16x32_bf16 v[116:119], v[132:135], v[196:199], v[116:119]
	v_mfma_f32_16x16x32_bf16 v[112:115], v[140:143], v[196:199], v[112:115]
	v_mfma_f32_16x16x32_bf16 v[108:111], v[132:135], v[204:207], v[108:111]
	v_mfma_f32_16x16x32_bf16 v[104:107], v[140:143], v[204:207], v[104:107]
	v_mfma_f32_16x16x32_bf16 v[100:103], v[132:135], v[212:215], v[100:103]
	v_mfma_f32_16x16x32_bf16 v[96:99], v[140:143], v[212:215], v[96:99]
	s_setprio 0
	s_setprio 1
	v_mfma_f32_16x16x32_bf16 v[60:63], v[144:147], v[184:187], v[60:63]
	v_mfma_f32_16x16x32_bf16 v[56:59], v[170:173], v[184:187], v[56:59]
	v_mfma_f32_16x16x32_bf16 v[52:55], v[144:147], v[192:195], v[52:55]
	v_mfma_f32_16x16x32_bf16 v[48:51], v[170:173], v[192:195], v[48:51]
	v_mfma_f32_16x16x32_bf16 v[44:47], v[144:147], v[200:203], v[44:47]
	v_mfma_f32_16x16x32_bf16 v[40:43], v[170:173], v[200:203], v[40:43]
	v_mfma_f32_16x16x32_bf16 v[36:39], v[144:147], v[208:211], v[36:39]
	v_mfma_f32_16x16x32_bf16 v[32:35], v[170:173], v[208:211], v[32:35]
	v_mfma_f32_16x16x32_bf16 v[60:63], v[166:169], v[188:191], v[60:63]
	v_mfma_f32_16x16x32_bf16 v[56:59], v[174:177], v[188:191], v[56:59]
	v_mfma_f32_16x16x32_bf16 v[52:55], v[166:169], v[196:199], v[52:55]
	v_mfma_f32_16x16x32_bf16 v[48:51], v[174:177], v[196:199], v[48:51]
	v_mfma_f32_16x16x32_bf16 v[44:47], v[166:169], v[204:207], v[44:47]
	v_mfma_f32_16x16x32_bf16 v[40:43], v[174:177], v[204:207], v[40:43]
	v_mfma_f32_16x16x32_bf16 v[36:39], v[166:169], v[212:215], v[36:39]
	v_mfma_f32_16x16x32_bf16 v[32:35], v[174:177], v[212:215], v[32:35]
	s_setprio 0
	s_barrier
	s_add_i32 s33, s33, s58
	s_mov_b32 m0, s33
	ds_read_b128 v[184:187], v183 offset:49152
	ds_read_b128 v[188:191], v183 offset:50176
	ds_read_b128 v[192:195], v183 offset:51200
	ds_read_b128 v[196:199], v183 offset:52224
	ds_read_b128 v[200:203], v183 offset:53248
	ds_read_b128 v[204:207], v183 offset:54272
	ds_read_b128 v[208:211], v183 offset:55296
	ds_read_b128 v[212:215], v183 offset:56320
	global_load_lds_dwordx4 v150, s[86:87]
	s_add_i32 m0, s33, 0x2000
	s_add_u32 s52, s52, 0x40080
	s_addc_u32 s53, s53, 0
	s_add_i32 s33, s34, s58
	global_load_lds_dwordx4 v156, s[86:87]
	s_mov_b32 m0, s33
	s_nop 0
	global_load_lds_dwordx4 v150, s[52:53]
	s_add_i32 m0, s33, 0x2000
	s_nop 0
	global_load_lds_dwordx4 v156, s[52:53]
	s_mov_b32 m0, s67
	s_nop 0
	global_load_lds_dwordx4 v148, s[88:89]
	s_mov_b32 m0, s68
	s_nop 0
	global_load_lds_dwordx4 v154, s[88:89]
	s_waitcnt vmcnt(8)
	s_waitcnt lgkmcnt(0)
	s_barrier
	s_setprio 1
	s_waitcnt lgkmcnt(0)
	v_mfma_f32_16x16x32_bf16 v[92:95], v[128:131], v[184:187], v[92:95]
	v_mfma_f32_16x16x32_bf16 v[88:91], v[136:139], v[184:187], v[88:91]
	v_mfma_f32_16x16x32_bf16 v[84:87], v[128:131], v[192:195], v[84:87]
	v_mfma_f32_16x16x32_bf16 v[80:83], v[136:139], v[192:195], v[80:83]
	v_mfma_f32_16x16x32_bf16 v[76:79], v[128:131], v[200:203], v[76:79]
	v_mfma_f32_16x16x32_bf16 v[72:75], v[136:139], v[200:203], v[72:75]
	v_mfma_f32_16x16x32_bf16 v[68:71], v[128:131], v[208:211], v[68:71]
	v_mfma_f32_16x16x32_bf16 v[64:67], v[136:139], v[208:211], v[64:67]
	v_mfma_f32_16x16x32_bf16 v[92:95], v[132:135], v[188:191], v[92:95]
	v_mfma_f32_16x16x32_bf16 v[88:91], v[140:143], v[188:191], v[88:91]
	v_mfma_f32_16x16x32_bf16 v[84:87], v[132:135], v[196:199], v[84:87]
	v_mfma_f32_16x16x32_bf16 v[80:83], v[140:143], v[196:199], v[80:83]
	v_mfma_f32_16x16x32_bf16 v[76:79], v[132:135], v[204:207], v[76:79]
	v_mfma_f32_16x16x32_bf16 v[72:75], v[140:143], v[204:207], v[72:75]
	v_mfma_f32_16x16x32_bf16 v[68:71], v[132:135], v[212:215], v[68:71]
	v_mfma_f32_16x16x32_bf16 v[64:67], v[140:143], v[212:215], v[64:67]
	s_setprio 0
	s_setprio 1
	v_mfma_f32_16x16x32_bf16 v[28:31], v[144:147], v[184:187], v[28:31]
	v_mfma_f32_16x16x32_bf16 v[24:27], v[170:173], v[184:187], v[24:27]
	v_mfma_f32_16x16x32_bf16 v[20:23], v[144:147], v[192:195], v[20:23]
	v_mfma_f32_16x16x32_bf16 v[16:19], v[170:173], v[192:195], v[16:19]
	v_mfma_f32_16x16x32_bf16 v[12:15], v[144:147], v[200:203], v[12:15]
	v_mfma_f32_16x16x32_bf16 v[8:11], v[170:173], v[200:203], v[8:11]
	v_mfma_f32_16x16x32_bf16 v[4:7], v[144:147], v[208:211], v[4:7]
	v_mfma_f32_16x16x32_bf16 v[0:3], v[170:173], v[208:211], v[0:3]
	v_mfma_f32_16x16x32_bf16 v[28:31], v[166:169], v[188:191], v[28:31]
	v_mfma_f32_16x16x32_bf16 v[24:27], v[174:177], v[188:191], v[24:27]
	v_mfma_f32_16x16x32_bf16 v[20:23], v[166:169], v[196:199], v[20:23]
	v_mfma_f32_16x16x32_bf16 v[16:19], v[174:177], v[196:199], v[16:19]
	v_mfma_f32_16x16x32_bf16 v[12:15], v[166:169], v[204:207], v[12:15]
	v_mfma_f32_16x16x32_bf16 v[8:11], v[174:177], v[204:207], v[8:11]
	v_mfma_f32_16x16x32_bf16 v[4:7], v[166:169], v[212:215], v[4:7]
	v_mfma_f32_16x16x32_bf16 v[0:3], v[174:177], v[212:215], v[0:3]
	s_setprio 0
	s_barrier
	s_add_i32 s80, s80, 2
	s_add_u32 s4, s4, 0x100
	s_addc_u32 s5, s5, 0
	s_add_u32 s78, s78, 0x100
	s_addc_u32 s79, s79, 0
	s_cmp_gt_u32 s80, 13
	s_cbranch_scc0 .LBB0_1210
	s_and_b64 vcc, exec, s[22:23]
	s_cbranch_vccz .LBB0_1213
	s_barrier

; #define PG8_STAGE(bufoff, gbase, voff) do { _Pragma("unroll") for (int _i = 0; _i < 2; ++_i) \
;         __builtin_amdgcn_global_load_lds((const unsigned*)((const char*)(gbase) + (voff)[_i]), (PG8_LAS unsigned*)(lds + (bufoff) + ldsw + _i * 8192), 16, 0, 0); } while (0)
; #define PG8_LDA(dst, b, h) do { _Pragma("unroll") for (int m = 0; m < 4; ++m) _Pragma("unroll") for (int k = 0; k < 2; ++k) dst[m][k] = *(const PG8_LAS bf16x8*)(lds + PG8_SA(b, h) + aoff + m * 2048 + k * 1024); } while (0)
; #define PG8_LDB(dst, b, h) do { _Pragma("unroll") for (int n = 0; n < 2; ++n) _Pragma("unroll") for (int k = 0; k < 2; ++k) dst[n][k] = *(const PG8_LAS bf16x8*)(lds + PG8_SB(b, h) + boff + n * 2048 + k * 1024); } while (0)
; #define PG8_MMA(ai, bj, At, Bt) do { __builtin_amdgcn_s_setprio(1); _Pragma("unroll") for (int m = 0; m < 4; ++m) _Pragma("unroll") for (int n = 0; n < 2; ++n) _Pragma("unroll") for (int k = 0; k < 2; ++k) \
;         acc[ai][bj][m][n] = __builtin_amdgcn_mfma_f32_16x16x32_bf16(Bt[n][k], At[m][k], acc[ai][bj][m][n], 0, 0, 0); __builtin_amdgcn_s_setprio(0); } while (0)
; #define PG8_WAIT_V(n) asm volatile("s_waitcnt vmcnt(" #n ")" ::: "memory")
; #define PG8_WAIT_L(n) asm volatile("s_waitcnt lgkmcnt(" #n ")" ::: "memory")
; template <class Epi, class Sched, bool ALIGN_EPI = false, bool SP2 = false>
; __device__ __forceinline__ void gemm_phase(PG8_LAS unsigned char* lds, const Gemm g, const Sched& S, const Epi& E) {
;     ...
;             const bool last = (t == nt - 2);
;             const char* a1 = cA + (size_t)(t + 1) * kstep;
;             const char* a2 = last ? nA : cA + (size_t)(t + 2) * kstep; const char* b2 = last ? nB : cB + (size_t)(t + 2) * kstep;
;             const char* a3 = a2 + kstep; const char* b3 = b2 + kstep;
;             if (last && has_next) S.a_ready(nxt);
;             if constexpr (SP2) {
;             PG8_LDB(B0, 0, 0); PG8_LDB(B1, 0, 1); PG8_SCHED; PG8_LDA(At, 0, 0); PG8_STAGE(PG8_SA(1, 1), a1 + hstep, voffA);
;             PG8_WAIT_V(8); PG8_WAIT_L(0); PG8_BAR; PG8_MMA(0, 0, At, B0); PG8_MMA(0, 1, At, B1); PG8_BAR; PG8_SCHED;
;             PG8_LDA(At, 0, 1); PG8_STAGE(PG8_SB(0, 0), b2, voffB); PG8_STAGE(PG8_SB(0, 1), b2 + hstep, voffB); PG8_STAGE(PG8_SA(0, 0), a2, voffA);
;             PG8_WAIT_V(8); PG8_WAIT_L(0); PG8_BAR; PG8_MMA(1, 0, At, B0); PG8_MMA(1, 1, At, B1); PG8_BAR; PG8_SCHED;
.LBB0_1417:
	ds_read_b128 v[128:131], v161
	ds_read_b128 v[132:135], v161 offset:1024
	ds_read_b128 v[152:155], v161 offset:2048
	ds_read_b128 v[164:167], v161 offset:3072
	ds_read_b128 v[168:171], v162
	ds_read_b128 v[172:175], v162 offset:1024
	ds_read_b128 v[176:179], v162 offset:2048
	ds_read_b128 v[180:183], v162 offset:3072
	s_add_u32 s28, s24, 0xfff50080
	s_addc_u32 s29, s25, -1
	s_cmp_eq_u32 s57, 40
	s_cselect_b32 s31, s5, s29
	s_cselect_b32 s30, s4, s28
	s_cselect_b32 s29, s23, s56
	s_cselect_b32 s28, s22, s55
	s_add_i32 m0, s39, 0xc000
	ds_read_b128 v[184:187], v163
	ds_read_b128 v[188:191], v163 offset:1024
	ds_read_b128 v[192:195], v163 offset:2048
	ds_read_b128 v[196:199], v163 offset:3072
	ds_read_b128 v[200:203], v163 offset:4096
	ds_read_b128 v[204:207], v163 offset:5120
	ds_read_b128 v[208:211], v163 offset:6144
	ds_read_b128 v[212:215], v163 offset:7168
	global_load_lds_dwordx4 v144, s[24:25]
	s_add_i32 m0, s39, 0xe000
	s_nop 0
	global_load_lds_dwordx4 v146, s[24:25]
	s_waitcnt vmcnt(8)
	s_waitcnt lgkmcnt(0)
	s_barrier
	s_setprio 1
	s_waitcnt lgkmcnt(0)
	v_mfma_f32_16x16x32_bf16 v[124:127], v[128:131], v[184:187], v[124:127]
	v_mfma_f32_16x16x32_bf16 v[120:123], v[152:155], v[184:187], v[120:123]
	v_mfma_f32_16x16x32_bf16 v[116:119], v[128:131], v[192:195], v[116:119]
	v_mfma_f32_16x16x32_bf16 v[112:115], v[152:155], v[192:195], v[112:115]
	v_mfma_f32_16x16x32_bf16 v[108:111], v[128:131], v[200:203], v[108:111]
	v_mfma_f32_16x16x32_bf16 v[104:107], v[152:155], v[200:203], v[104:107]
	v_mfma_f32_16x16x32_bf16 v[100:103], v[128:131], v[208:211], v[100:103]
	v_mfma_f32_16x16x32_bf16 v[96:99], v[152:155], v[208:211], v[96:99]
	v_mfma_f32_16x16x32_bf16 v[124:127], v[132:135], v[188:191], v[124:127]
	v_mfma_f32_16x16x32_bf16 v[120:123], v[164:167], v[188:191], v[120:123]
	v_mfma_f32_16x16x32_bf16 v[116:119], v[132:135], v[196:199], v[116:119]
	v_mfma_f32_16x16x32_bf16 v[112:115], v[164:167], v[196:199], v[112:115]
	v_mfma_f32_16x16x32_bf16 v[108:111], v[132:135], v[204:207], v[108:111]
	v_mfma_f32_16x16x32_bf16 v[104:107], v[164:167], v[204:207], v[104:107]
	v_mfma_f32_16x16x32_bf16 v[100:103], v[132:135], v[212:215], v[100:103]
	v_mfma_f32_16x16x32_bf16 v[96:99], v[164:167], v[212:215], v[96:99]
	s_setprio 0
	s_setprio 1
	v_mfma_f32_16x16x32_bf16 v[64:67], v[168:171], v[184:187], v[64:67]
	v_mfma_f32_16x16x32_bf16 v[56:59], v[176:179], v[184:187], v[56:59]
	v_mfma_f32_16x16x32_bf16 v[52:55], v[168:171], v[192:195], v[52:55]
	v_mfma_f32_16x16x32_bf16 v[48:51], v[176:179], v[192:195], v[48:51]
	v_mfma_f32_16x16x32_bf16 v[44:47], v[168:171], v[200:203], v[44:47]
	v_mfma_f32_16x16x32_bf16 v[40:43], v[176:179], v[200:203], v[40:43]
	v_mfma_f32_16x16x32_bf16 v[36:39], v[168:171], v[208:211], v[36:39]
	v_mfma_f32_16x16x32_bf16 v[32:35], v[176:179], v[208:211], v[32:35]
	v_mfma_f32_16x16x32_bf16 v[64:67], v[172:175], v[188:191], v[64:67]
	v_mfma_f32_16x16x32_bf16 v[56:59], v[180:183], v[188:191], v[56:59]
	v_mfma_f32_16x16x32_bf16 v[52:55], v[172:175], v[196:199], v[52:55]
	v_mfma_f32_16x16x32_bf16 v[48:51], v[180:183], v[196:199], v[48:51]
	v_mfma_f32_16x16x32_bf16 v[44:47], v[172:175], v[204:207], v[44:47]
	v_mfma_f32_16x16x32_bf16 v[40:43], v[180:183], v[204:207], v[40:43]
	v_mfma_f32_16x16x32_bf16 v[36:39], v[172:175], v[212:215], v[36:39]
	v_mfma_f32_16x16x32_bf16 v[32:35], v[180:183], v[212:215], v[32:35]
	s_setprio 0
	s_barrier
	s_add_i32 s58, s49, s37
	s_add_u32 s62, s28, s10
	s_addc_u32 s63, s29, s11
	s_mov_b32 m0, s58
	ds_read_b128 v[184:187], v163 offset:16384
	ds_read_b128 v[188:191], v163 offset:17408
	ds_read_b128 v[192:195], v163 offset:18432
	ds_read_b128 v[196:199], v163 offset:19456
	ds_read_b128 v[200:203], v163 offset:20480
	ds_read_b128 v[204:207], v163 offset:21504
	ds_read_b128 v[208:211], v163 offset:22528
	ds_read_b128 v[212:215], v163 offset:23552
	global_load_lds_dwordx4 v138, s[28:29]
	s_add_i32 m0, s58, 0x2000
	s_add_u32 s58, s28, 0xb0000
	s_addc_u32 s59, s29, 0
	s_add_i32 s60, s50, s37
	global_load_lds_dwordx4 v142, s[28:29]
	s_mov_b32 m0, s60
	s_add_u32 s64, s30, s10
	s_addc_u32 s65, s31, s11
	global_load_lds_dwordx4 v138, s[58:59]
	s_add_i32 m0, s60, 0x2000
	s_nop 0
	global_load_lds_dwordx4 v142, s[58:59]
	s_mov_b32 m0, s39
	s_nop 0
	global_load_lds_dwordx4 v136, s[30:31]
	s_mov_b32 m0, s40
	s_nop 0
	global_load_lds_dwordx4 v140, s[30:31]
	s_waitcnt vmcnt(8)
	s_waitcnt lgkmcnt(0)
	s_barrier
	s_setprio 1
	s_waitcnt lgkmcnt(0)
	v_mfma_f32_16x16x32_bf16 v[92:95], v[128:131], v[184:187], v[92:95]
	v_mfma_f32_16x16x32_bf16 v[88:91], v[152:155], v[184:187], v[88:91]
	v_mfma_f32_16x16x32_bf16 v[84:87], v[128:131], v[192:195], v[84:87]
	v_mfma_f32_16x16x32_bf16 v[80:83], v[152:155], v[192:195], v[80:83]
	v_mfma_f32_16x16x32_bf16 v[76:79], v[128:131], v[200:203], v[76:79]
	v_mfma_f32_16x16x32_bf16 v[72:75], v[152:155], v[200:203], v[72:75]
	v_mfma_f32_16x16x32_bf16 v[68:71], v[128:131], v[208:211], v[68:71]
	v_mfma_f32_16x16x32_bf16 v[60:63], v[152:155], v[208:211], v[60:63]
	v_mfma_f32_16x16x32_bf16 v[92:95], v[132:135], v[188:191], v[92:95]
	v_mfma_f32_16x16x32_bf16 v[88:91], v[164:167], v[188:191], v[88:91]
	v_mfma_f32_16x16x32_bf16 v[84:87], v[132:135], v[196:199], v[84:87]
	v_mfma_f32_16x16x32_bf16 v[80:83], v[164:167], v[196:199], v[80:83]
	v_mfma_f32_16x16x32_bf16 v[76:79], v[132:135], v[204:207], v[76:79]
	v_mfma_f32_16x16x32_bf16 v[72:75], v[164:167], v[204:207], v[72:75]
	v_mfma_f32_16x16x32_bf16 v[68:71], v[132:135], v[212:215], v[68:71]
	v_mfma_f32_16x16x32_bf16 v[60:63], v[164:167], v[212:215], v[60:63]
	s_setprio 0
	s_setprio 1
	v_mfma_f32_16x16x32_bf16 v[28:31], v[168:171], v[184:187], v[28:31]
	v_mfma_f32_16x16x32_bf16 v[24:27], v[176:179], v[184:187], v[24:27]
	v_mfma_f32_16x16x32_bf16 v[20:23], v[168:171], v[192:195], v[20:23]
	v_mfma_f32_16x16x32_bf16 v[16:19], v[176:179], v[192:195], v[16:19]
	v_mfma_f32_16x16x32_bf16 v[12:15], v[168:171], v[200:203], v[12:15]
	v_mfma_f32_16x16x32_bf16 v[8:11], v[176:179], v[200:203], v[8:11]
	v_mfma_f32_16x16x32_bf16 v[4:7], v[168:171], v[208:211], v[4:7]
	v_mfma_f32_16x16x32_bf16 v[0:3], v[176:179], v[208:211], v[0:3]
	v_mfma_f32_16x16x32_bf16 v[28:31], v[172:175], v[188:191], v[28:31]
	v_mfma_f32_16x16x32_bf16 v[24:27], v[180:183], v[188:191], v[24:27]
	v_mfma_f32_16x16x32_bf16 v[20:23], v[172:175], v[196:199], v[20:23]
	v_mfma_f32_16x16x32_bf16 v[16:19], v[180:183], v[196:199], v[16:19]
	v_mfma_f32_16x16x32_bf16 v[12:15], v[172:175], v[204:207], v[12:15]
	v_mfma_f32_16x16x32_bf16 v[8:11], v[180:183], v[204:207], v[8:11]
	v_mfma_f32_16x16x32_bf16 v[4:7], v[172:175], v[212:215], v[4:7]
	v_mfma_f32_16x16x32_bf16 v[0:3], v[180:183], v[212:215], v[0:3]
	s_setprio 0
	s_barrier
; #define PG8_STAGE(bufoff, gbase, voff) do { _Pragma("unroll") for (int _i = 0; _i < 2; ++_i) \
;         __builtin_amdgcn_global_load_lds((const unsigned*)((const char*)(gbase) + (voff)[_i]), (PG8_LAS unsigned*)(lds + (bufoff) + ldsw + _i * 8192), 16, 0, 0); } while (0)
; #define PG8_LDA(dst, b, h) do { _Pragma("unroll") for (int m = 0; m < 4; ++m) _Pragma("unroll") for (int k = 0; k < 2; ++k) dst[m][k] = *(const PG8_LAS bf16x8*)(lds + PG8_SA(b, h) + aoff + m * 2048 + k * 1024); } while (0)
; #define PG8_LDB(dst, b, h) do { _Pragma("unroll") for (int n = 0; n < 2; ++n) _Pragma("unroll") for (int k = 0; k < 2; ++k) dst[n][k] = *(const PG8_LAS bf16x8*)(lds + PG8_SB(b, h) + boff + n * 2048 + k * 1024); } while (0)
; template <class Epi, class Sched, bool ALIGN_EPI = false, bool SP2 = false>
; __device__ __forceinline__ void gemm_phase(PG8_LAS unsigned char* lds, const Gemm g, const Sched& S, const Epi& E) {
;     ...
;         for (int t = 0; t < nt; t += 2) {
;             const bool last = (t == nt - 2);
;             const char* a1 = cA + (size_t)(t + 1) * kstep;
;             const char* a2 = last ? nA : cA + (size_t)(t + 2) * kstep; const char* b2 = last ? nB : cB + (size_t)(t + 2) * kstep;
;             const char* a3 = a2 + kstep; const char* b3 = b2 + kstep;
;             if (last && has_next) S.a_ready(nxt);
;             if constexpr (SP2) {
;             PG8_LDB(B0, 0, 0); PG8_LDB(B1, 0, 1); PG8_SCHED; PG8_LDA(At, 0, 0); PG8_STAGE(PG8_SA(1, 1), a1 + hstep, voffA);
;             PG8_WAIT_V(8); PG8_WAIT_L(0); PG8_BAR; PG8_MMA(0, 0, At, B0); PG8_MMA(0, 1, At, B1); PG8_BAR; PG8_SCHED;
;             PG8_LDA(At, 0, 1); PG8_STAGE(PG8_SB(0, 0), b2, voffB); PG8_STAGE(PG8_SB(0, 1), b2 + hstep, voffB); PG8_STAGE(PG8_SA(0, 0), a2, voffA);
;             PG8_WAIT_V(8); PG8_WAIT_L(0); PG8_BAR; PG8_MMA(1, 0, At, B0); PG8_MMA(1, 1, At, B1); PG8_BAR; PG8_SCHED;
;             PG8_LDB(B0, 1, 0); PG8_LDB(B1, 1, 1); PG8_SCHED; PG8_LDA(At, 1, 0); PG8_STAGE(PG8_SA(0, 1), a2 + hstep, voffA);
;             PG8_WAIT_V(8); PG8_WAIT_L(0); PG8_BAR; PG8_MMA(0, 0, At, B0); PG8_MMA(0, 1, At, B1); PG8_BAR; PG8_SCHED;
;             PG8_LDA(At, 1, 1); PG8_STAGE(PG8_SB(1, 0), b3, voffB); PG8_STAGE(PG8_SB(1, 1), b3 + hstep, voffB); PG8_STAGE(PG8_SA(1, 0), a3, voffA);
;             PG8_WAIT_V(8); PG8_WAIT_L(0); PG8_BAR; PG8_MMA(1, 0, At, B0); PG8_MMA(1, 1, At, B1); PG8_BAR; PG8_SCHED;
	s_add_i32 s58, 0, 0x18000
	s_add_i32 s59, 0, 0x1c000
	v_add_u32_e32 v164, s58, v159
	v_add_u32_e32 v180, s59, v159
	ds_read_b128 v[128:131], v164
	ds_read_b128 v[132:135], v164 offset:1024
	ds_read_b128 v[152:155], v164 offset:2048
	ds_read_b128 v[164:167], v164 offset:3072
	ds_read_b128 v[168:171], v180
	ds_read_b128 v[172:175], v180 offset:1024
	ds_read_b128 v[176:179], v180 offset:2048
	ds_read_b128 v[180:183], v180 offset:3072
	s_add_u32 s30, s30, 0xb0000
	s_addc_u32 s31, s31, 0
	s_mov_b32 m0, s41
	ds_read_b128 v[184:187], v163 offset:32768
	ds_read_b128 v[188:191], v163 offset:33792
	ds_read_b128 v[192:195], v163 offset:34816
	ds_read_b128 v[196:199], v163 offset:35840
	ds_read_b128 v[200:203], v163 offset:36864
	ds_read_b128 v[204:207], v163 offset:37888
	ds_read_b128 v[208:211], v163 offset:38912
	ds_read_b128 v[212:215], v163 offset:39936
	global_load_lds_dwordx4 v136, s[30:31]
	s_mov_b32 m0, s42
	s_nop 0
	global_load_lds_dwordx4 v140, s[30:31]
	s_waitcnt vmcnt(8)
	s_waitcnt lgkmcnt(0)
	s_barrier
	s_setprio 1
	s_waitcnt lgkmcnt(0)
	v_mfma_f32_16x16x32_bf16 v[124:127], v[128:131], v[184:187], v[124:127]
	v_mfma_f32_16x16x32_bf16 v[120:123], v[152:155], v[184:187], v[120:123]
	v_mfma_f32_16x16x32_bf16 v[116:119], v[128:131], v[192:195], v[116:119]
	v_mfma_f32_16x16x32_bf16 v[112:115], v[152:155], v[192:195], v[112:115]
	v_mfma_f32_16x16x32_bf16 v[108:111], v[128:131], v[200:203], v[108:111]
	v_mfma_f32_16x16x32_bf16 v[104:107], v[152:155], v[200:203], v[104:107]
	v_mfma_f32_16x16x32_bf16 v[100:103], v[128:131], v[208:211], v[100:103]
	v_mfma_f32_16x16x32_bf16 v[96:99], v[152:155], v[208:211], v[96:99]
	v_mfma_f32_16x16x32_bf16 v[124:127], v[132:135], v[188:191], v[124:127]
	v_mfma_f32_16x16x32_bf16 v[120:123], v[164:167], v[188:191], v[120:123]
	v_mfma_f32_16x16x32_bf16 v[116:119], v[132:135], v[196:199], v[116:119]
	v_mfma_f32_16x16x32_bf16 v[112:115], v[164:167], v[196:199], v[112:115]
	v_mfma_f32_16x16x32_bf16 v[108:111], v[132:135], v[204:207], v[108:111]
	v_mfma_f32_16x16x32_bf16 v[104:107], v[164:167], v[204:207], v[104:107]
	v_mfma_f32_16x16x32_bf16 v[100:103], v[132:135], v[212:215], v[100:103]
	v_mfma_f32_16x16x32_bf16 v[96:99], v[164:167], v[212:215], v[96:99]
	s_setprio 0
	s_setprio 1
	v_mfma_f32_16x16x32_bf16 v[64:67], v[168:171], v[184:187], v[64:67]
	v_mfma_f32_16x16x32_bf16 v[56:59], v[176:179], v[184:187], v[56:59]
	v_mfma_f32_16x16x32_bf16 v[52:55], v[168:171], v[192:195], v[52:55]
	v_mfma_f32_16x16x32_bf16 v[48:51], v[176:179], v[192:195], v[48:51]
	v_mfma_f32_16x16x32_bf16 v[44:47], v[168:171], v[200:203], v[44:47]
	v_mfma_f32_16x16x32_bf16 v[40:43], v[176:179], v[200:203], v[40:43]
	v_mfma_f32_16x16x32_bf16 v[36:39], v[168:171], v[208:211], v[36:39]
	v_mfma_f32_16x16x32_bf16 v[32:35], v[176:179], v[208:211], v[32:35]
	v_mfma_f32_16x16x32_bf16 v[64:67], v[172:175], v[188:191], v[64:67]
	v_mfma_f32_16x16x32_bf16 v[56:59], v[180:183], v[188:191], v[56:59]
	v_mfma_f32_16x16x32_bf16 v[52:55], v[172:175], v[196:199], v[52:55]
	v_mfma_f32_16x16x32_bf16 v[48:51], v[180:183], v[196:199], v[48:51]
	v_mfma_f32_16x16x32_bf16 v[44:47], v[172:175], v[204:207], v[44:47]
	v_mfma_f32_16x16x32_bf16 v[40:43], v[180:183], v[204:207], v[40:43]
	v_mfma_f32_16x16x32_bf16 v[36:39], v[172:175], v[212:215], v[36:39]
	v_mfma_f32_16x16x32_bf16 v[32:35], v[180:183], v[212:215], v[32:35]
	s_setprio 0
	s_barrier
	s_add_i32 s30, s58, s37
	s_mov_b32 m0, s30
	ds_read_b128 v[184:187], v163 offset:49152
	ds_read_b128 v[188:191], v163 offset:50176
	ds_read_b128 v[192:195], v163 offset:51200
	ds_read_b128 v[196:199], v163 offset:52224
	ds_read_b128 v[200:203], v163 offset:53248
	ds_read_b128 v[204:207], v163 offset:54272
	ds_read_b128 v[208:211], v163 offset:55296
	ds_read_b128 v[212:215], v163 offset:56320
	global_load_lds_dwordx4 v138, s[62:63]
	s_add_i32 m0, s30, 0x2000
	s_add_u32 s28, s28, 0xb0080
	s_addc_u32 s29, s29, 0
	s_add_i32 s30, s59, s37
	global_load_lds_dwordx4 v142, s[62:63]
	s_mov_b32 m0, s30
	s_nop 0
	global_load_lds_dwordx4 v138, s[28:29]
	s_add_i32 m0, s30, 0x2000
	s_nop 0
	global_load_lds_dwordx4 v142, s[28:29]
	s_mov_b32 m0, s47
	s_nop 0
	global_load_lds_dwordx4 v136, s[64:65]
	s_mov_b32 m0, s48
	s_nop 0
	global_load_lds_dwordx4 v140, s[64:65]
	s_waitcnt vmcnt(8)
	s_waitcnt lgkmcnt(0)
	s_barrier
	s_setprio 1
	s_waitcnt lgkmcnt(0)
	v_mfma_f32_16x16x32_bf16 v[92:95], v[128:131], v[184:187], v[92:95]
	v_mfma_f32_16x16x32_bf16 v[88:91], v[152:155], v[184:187], v[88:91]
	v_mfma_f32_16x16x32_bf16 v[84:87], v[128:131], v[192:195], v[84:87]
	v_mfma_f32_16x16x32_bf16 v[80:83], v[152:155], v[192:195], v[80:83]
	v_mfma_f32_16x16x32_bf16 v[76:79], v[128:131], v[200:203], v[76:79]
	v_mfma_f32_16x16x32_bf16 v[72:75], v[152:155], v[200:203], v[72:75]
	v_mfma_f32_16x16x32_bf16 v[68:71], v[128:131], v[208:211], v[68:71]
	v_mfma_f32_16x16x32_bf16 v[60:63], v[152:155], v[208:211], v[60:63]
	v_mfma_f32_16x16x32_bf16 v[92:95], v[132:135], v[188:191], v[92:95]
	v_mfma_f32_16x16x32_bf16 v[88:91], v[164:167], v[188:191], v[88:91]
	v_mfma_f32_16x16x32_bf16 v[84:87], v[132:135], v[196:199], v[84:87]
	v_mfma_f32_16x16x32_bf16 v[80:83], v[164:167], v[196:199], v[80:83]
	v_mfma_f32_16x16x32_bf16 v[76:79], v[132:135], v[204:207], v[76:79]
	v_mfma_f32_16x16x32_bf16 v[72:75], v[164:167], v[204:207], v[72:75]
	v_mfma_f32_16x16x32_bf16 v[68:71], v[132:135], v[212:215], v[68:71]
	v_mfma_f32_16x16x32_bf16 v[60:63], v[164:167], v[212:215], v[60:63]
	s_setprio 0
	s_setprio 1
	v_mfma_f32_16x16x32_bf16 v[28:31], v[168:171], v[184:187], v[28:31]
	v_mfma_f32_16x16x32_bf16 v[24:27], v[176:179], v[184:187], v[24:27]
	v_mfma_f32_16x16x32_bf16 v[20:23], v[168:171], v[192:195], v[20:23]
	v_mfma_f32_16x16x32_bf16 v[16:19], v[176:179], v[192:195], v[16:19]
	v_mfma_f32_16x16x32_bf16 v[12:15], v[168:171], v[200:203], v[12:15]
	v_mfma_f32_16x16x32_bf16 v[8:11], v[176:179], v[200:203], v[8:11]
	v_mfma_f32_16x16x32_bf16 v[4:7], v[168:171], v[208:211], v[4:7]
	v_mfma_f32_16x16x32_bf16 v[0:3], v[176:179], v[208:211], v[0:3]
	v_mfma_f32_16x16x32_bf16 v[28:31], v[172:175], v[188:191], v[28:31]
	v_mfma_f32_16x16x32_bf16 v[24:27], v[180:183], v[188:191], v[24:27]
	v_mfma_f32_16x16x32_bf16 v[20:23], v[172:175], v[196:199], v[20:23]
	v_mfma_f32_16x16x32_bf16 v[16:19], v[180:183], v[196:199], v[16:19]
	v_mfma_f32_16x16x32_bf16 v[12:15], v[172:175], v[204:207], v[12:15]
	v_mfma_f32_16x16x32_bf16 v[8:11], v[180:183], v[204:207], v[8:11]
	v_mfma_f32_16x16x32_bf16 v[4:7], v[172:175], v[212:215], v[4:7]
	v_mfma_f32_16x16x32_bf16 v[0:3], v[180:183], v[212:215], v[0:3]
	s_setprio 0
	s_barrier
	s_add_i32 s57, s57, 2
	s_add_u32 s24, s24, 0x100
	s_addc_u32 s25, s25, 0
	s_add_u32 s55, s55, 0x100
	s_addc_u32 s56, s56, 0
	s_cmp_gt_u32 s57, 41
	s_cbranch_scc0 .LBB0_1417
	s_and_b64 vcc, exec, s[12:13]
	s_cbranch_vccz .LBB0_1420
	s_barrier
